# GEMM K-loops (4 sites): back edge rotated - loop counter, exit test and next-iteration address SALU moved in front of the loop-back barrier, branch re-enters after the head SALU
# baseline (speedup 1.0000x reference)
; #define PG8_STAGE(bufoff, gbase, voff) do { _Pragma("unroll") for (int _i = 0; _i < 2; ++_i) \
;         __builtin_amdgcn_global_load_lds((const unsigned*)((const char*)(gbase) + (voff)[_i]), (PG8_LAS unsigned*)(lds + (bufoff) + ldsw + _i * 8192), 16, 0, 0); } while (0)
; #define PG8_LDA(dst, b, h) do { _Pragma("unroll") for (int m = 0; m < 4; ++m) _Pragma("unroll") for (int k = 0; k < 2; ++k) dst[m][k] = *(const PG8_LAS bf16x8*)(lds + PG8_SA(b, h) + aoff + m * 2048 + k * 1024); } while (0)
; #define PG8_LDB(dst, b, h) do { _Pragma("unroll") for (int n = 0; n < 2; ++n) _Pragma("unroll") for (int k = 0; k < 2; ++k) dst[n][k] = *(const PG8_LAS bf16x8*)(lds + PG8_SB(b, h) + boff + n * 2048 + k * 1024); } while (0)
; #define PG8_MMA(ai, bj, At, Bt) do { __builtin_amdgcn_s_setprio(1); _Pragma("unroll") for (int m = 0; m < 4; ++m) _Pragma("unroll") for (int n = 0; n < 2; ++n) _Pragma("unroll") for (int k = 0; k < 2; ++k) \
;         acc[ai][bj][m][n] = __builtin_amdgcn_mfma_f32_16x16x32_bf16(Bt[n][k], At[m][k], acc[ai][bj][m][n], 0, 0, 0); __builtin_amdgcn_s_setprio(0); } while (0)
; #define PG8_WAIT_V(n) asm volatile("s_waitcnt vmcnt(" #n ")" ::: "memory")
; #define PG8_BAR __builtin_amdgcn_s_barrier()
; template <class Epi, class Sched, bool ALIGN_EPI = false, bool SP2 = false>
; __device__ __forceinline__ void gemm_phase(PG8_LAS unsigned char* lds, const Gemm g, const Sched& S, const Epi& E) {
;     ...
;         for (int t = 0; t < nt; t += 2) {
;             const bool last = (t == nt - 2);
;             const char* a1 = cA + (size_t)(t + 1) * kstep;
;             const char* a2 = last ? nA : cA + (size_t)(t + 2) * kstep; const char* b2 = last ? nB : cB + (size_t)(t + 2) * kstep;
;             const char* a3 = a2 + kstep; const char* b3 = b2 + kstep;
;             if (last && has_next) S.a_ready(nxt);
;             if constexpr (SP2) {
;             PG8_LDB(B0, 0, 0); PG8_LDB(B1, 0, 1); PG8_SCHED; PG8_LDA(At, 0, 0); PG8_STAGE(PG8_SA(1, 1), a1 + hstep, voffA);
;             PG8_WAIT_V(8); PG8_WAIT_L(0); PG8_BAR; PG8_MMA(0, 0, At, B0); PG8_MMA(0, 1, At, B1); PG8_BAR; PG8_SCHED;
;             PG8_LDA(At, 0, 1); PG8_STAGE(PG8_SB(0, 0), b2, voffB); PG8_STAGE(PG8_SB(0, 1), b2 + hstep, voffB); PG8_STAGE(PG8_SA(0, 0), a2, voffA);
;             PG8_WAIT_V(8); PG8_WAIT_L(0); PG8_BAR; PG8_MMA(1, 0, At, B0); PG8_MMA(1, 1, At, B1); PG8_BAR; PG8_SCHED;
.LBB0_96:
	s_add_u32 s38, s30, 0xfffc0080
	s_addc_u32 s39, s31, -1
	s_add_i32 s75, 0, 0x10000
	s_cmp_eq_u32 s74, 12
	s_cselect_b32 s41, s5, s39
	s_cselect_b32 s40, s19, s38
	s_cselect_b32 s39, s17, s73
	s_cselect_b32 s38, s71, s72
	s_add_i32 s78, 0, 0x14000
.Lrot_ip:
	v_add_u32_e32 v146, s75, v150
	ds_read_b128 v[142:145], v146
	ds_read_b128 v[154:157], v146 offset:1024
	ds_read_b128 v[158:161], v146 offset:2048
	ds_read_b128 v[162:165], v146 offset:3072
	v_add_u32_e32 v146, s78, v150
	ds_read_b128 v[166:169], v146
	ds_read_b128 v[170:173], v146 offset:1024
	ds_read_b128 v[174:177], v146 offset:2048
	ds_read_b128 v[188:191], v146 offset:3072
	v_lshl_add_u64 v[146:147], s[30:31], 0, v[138:139]
	s_add_i32 m0, s25, 0xc000
	ds_read_b128 v[192:195], v152
	ds_read_b128 v[196:199], v152 offset:1024
	ds_read_b128 v[200:203], v152 offset:2048
	ds_read_b128 v[204:207], v152 offset:3072
	ds_read_b128 v[208:211], v152 offset:4096
	ds_read_b128 v[212:215], v152 offset:5120
	ds_read_b128 v[216:219], v152 offset:6144
	ds_read_b128 v[220:223], v152 offset:7168
	global_load_lds_dwordx4 v[146:147], off
	v_lshl_add_u64 v[146:147], s[30:31], 0, v[140:141]
	s_add_i32 m0, s25, 0xe000
	s_nop 0
	global_load_lds_dwordx4 v[146:147], off
	s_waitcnt vmcnt(8)
	s_waitcnt lgkmcnt(0)
	s_barrier
	s_setprio 1
	s_waitcnt lgkmcnt(0)
	v_mfma_f32_16x16x32_bf16 v[126:129], v[142:145], v[192:195], v[126:129]
	v_mfma_f32_16x16x32_bf16 v[122:125], v[158:161], v[192:195], v[122:125]
	v_mfma_f32_16x16x32_bf16 v[110:113], v[142:145], v[200:203], v[110:113]
	v_mfma_f32_16x16x32_bf16 v[106:109], v[158:161], v[200:203], v[106:109]
	v_mfma_f32_16x16x32_bf16 v[94:97], v[142:145], v[208:211], v[94:97]
	v_mfma_f32_16x16x32_bf16 v[90:93], v[158:161], v[208:211], v[90:93]
	v_mfma_f32_16x16x32_bf16 v[78:81], v[142:145], v[216:219], v[78:81]
	v_mfma_f32_16x16x32_bf16 v[74:77], v[158:161], v[216:219], v[74:77]
	v_mfma_f32_16x16x32_bf16 v[126:129], v[154:157], v[196:199], v[126:129]
	v_mfma_f32_16x16x32_bf16 v[122:125], v[162:165], v[196:199], v[122:125]
	v_mfma_f32_16x16x32_bf16 v[110:113], v[154:157], v[204:207], v[110:113]
	v_mfma_f32_16x16x32_bf16 v[106:109], v[162:165], v[204:207], v[106:109]
	v_mfma_f32_16x16x32_bf16 v[94:97], v[154:157], v[212:215], v[94:97]
	v_mfma_f32_16x16x32_bf16 v[90:93], v[162:165], v[212:215], v[90:93]
	v_mfma_f32_16x16x32_bf16 v[78:81], v[154:157], v[220:223], v[78:81]
	v_mfma_f32_16x16x32_bf16 v[74:77], v[162:165], v[220:223], v[74:77]
	s_setprio 0
	s_setprio 1
	v_mfma_f32_16x16x32_bf16 v[118:121], v[166:169], v[192:195], v[118:121]
	v_mfma_f32_16x16x32_bf16 v[114:117], v[174:177], v[192:195], v[114:117]
	v_mfma_f32_16x16x32_bf16 v[102:105], v[166:169], v[200:203], v[102:105]
	v_mfma_f32_16x16x32_bf16 v[98:101], v[174:177], v[200:203], v[98:101]
	v_mfma_f32_16x16x32_bf16 v[86:89], v[166:169], v[208:211], v[86:89]
	v_mfma_f32_16x16x32_bf16 v[82:85], v[174:177], v[208:211], v[82:85]
	v_mfma_f32_16x16x32_bf16 v[70:73], v[166:169], v[216:219], v[70:73]
	v_mfma_f32_16x16x32_bf16 v[66:69], v[174:177], v[216:219], v[66:69]
	v_mfma_f32_16x16x32_bf16 v[118:121], v[170:173], v[196:199], v[118:121]
	v_mfma_f32_16x16x32_bf16 v[114:117], v[188:191], v[196:199], v[114:117]
	v_mfma_f32_16x16x32_bf16 v[102:105], v[170:173], v[204:207], v[102:105]
	v_mfma_f32_16x16x32_bf16 v[98:101], v[188:191], v[204:207], v[98:101]
	v_mfma_f32_16x16x32_bf16 v[86:89], v[170:173], v[212:215], v[86:89]
	v_mfma_f32_16x16x32_bf16 v[82:85], v[188:191], v[212:215], v[82:85]
	v_mfma_f32_16x16x32_bf16 v[70:73], v[170:173], v[220:223], v[70:73]
	v_mfma_f32_16x16x32_bf16 v[66:69], v[188:191], v[220:223], v[66:69]
	s_setprio 0
	s_barrier
	s_add_i32 s75, s75, s47
	v_lshl_add_u64 v[146:147], s[38:39], 0, v[0:1]
	s_mov_b32 m0, s75
	ds_read_b128 v[192:195], v152 offset:16384
	ds_read_b128 v[196:199], v152 offset:17408
	ds_read_b128 v[200:203], v152 offset:18432
	ds_read_b128 v[204:207], v152 offset:19456
	ds_read_b128 v[208:211], v152 offset:20480
	ds_read_b128 v[212:215], v152 offset:21504
	ds_read_b128 v[216:219], v152 offset:22528
	ds_read_b128 v[220:223], v152 offset:23552
	global_load_lds_dwordx4 v[146:147], off
	s_add_i32 m0, s75, 0x2000
	s_add_u32 s76, s38, 0x40000
	v_lshl_add_u64 v[182:183], s[38:39], 0, v[134:135]
	s_addc_u32 s77, s39, 0
	s_add_i32 s75, s78, s47
	global_load_lds_dwordx4 v[182:183], off
	v_lshl_add_u64 v[184:185], s[76:77], 0, v[0:1]
	s_mov_b32 m0, s75
	v_lshl_add_u64 v[224:225], s[40:41], 0, v[132:133]
	global_load_lds_dwordx4 v[184:185], off
	v_lshl_add_u64 v[184:185], s[76:77], 0, v[134:135]
	s_add_i32 m0, s75, 0x2000
	s_nop 0
	global_load_lds_dwordx4 v[184:185], off
	v_lshl_add_u64 v[184:185], s[40:41], 0, v[130:131]
	s_mov_b32 m0, s25
	s_nop 0
	global_load_lds_dwordx4 v[184:185], off
	s_mov_b32 m0, s48
	s_nop 0
	global_load_lds_dwordx4 v[224:225], off
	s_waitcnt vmcnt(8)
	s_waitcnt lgkmcnt(0)
	s_barrier
; #define PG8_STAGE(bufoff, gbase, voff) do { _Pragma("unroll") for (int _i = 0; _i < 2; ++_i) \
;         __builtin_amdgcn_global_load_lds((const unsigned*)((const char*)(gbase) + (voff)[_i]), (PG8_LAS unsigned*)(lds + (bufoff) + ldsw + _i * 8192), 16, 0, 0); } while (0)
; #define PG8_LDA(dst, b, h) do { _Pragma("unroll") for (int m = 0; m < 4; ++m) _Pragma("unroll") for (int k = 0; k < 2; ++k) dst[m][k] = *(const PG8_LAS bf16x8*)(lds + PG8_SA(b, h) + aoff + m * 2048 + k * 1024); } while (0)
; #define PG8_LDB(dst, b, h) do { _Pragma("unroll") for (int n = 0; n < 2; ++n) _Pragma("unroll") for (int k = 0; k < 2; ++k) dst[n][k] = *(const PG8_LAS bf16x8*)(lds + PG8_SB(b, h) + boff + n * 2048 + k * 1024); } while (0)
; #define PG8_MMA(ai, bj, At, Bt) do { __builtin_amdgcn_s_setprio(1); _Pragma("unroll") for (int m = 0; m < 4; ++m) _Pragma("unroll") for (int n = 0; n < 2; ++n) _Pragma("unroll") for (int k = 0; k < 2; ++k) \
;         acc[ai][bj][m][n] = __builtin_amdgcn_mfma_f32_16x16x32_bf16(Bt[n][k], At[m][k], acc[ai][bj][m][n], 0, 0, 0); __builtin_amdgcn_s_setprio(0); } while (0)
; #define PG8_WAIT_V(n) asm volatile("s_waitcnt vmcnt(" #n ")" ::: "memory")
; #define PG8_WAIT_L(n) asm volatile("s_waitcnt lgkmcnt(" #n ")" ::: "memory")
; #define PG8_BAR __builtin_amdgcn_s_barrier()
; #define PG8_SCHED __builtin_amdgcn_sched_barrier(0)
; template <class Epi, class Sched, bool ALIGN_EPI = false, bool SP2 = false>
; __device__ __forceinline__ void gemm_phase(PG8_LAS unsigned char* lds, const Gemm g, const Sched& S, const Epi& E) {
;     ...
;             PG8_WAIT_V(8); PG8_WAIT_L(0); PG8_BAR; PG8_MMA(1, 0, At, B0); PG8_MMA(1, 1, At, B1); PG8_BAR; PG8_SCHED;
;             PG8_LDB(B0, 1, 0); PG8_LDB(B1, 1, 1); PG8_SCHED; PG8_LDA(At, 1, 0); PG8_STAGE(PG8_SA(0, 1), a2 + hstep, voffA);
;             PG8_WAIT_V(8); PG8_WAIT_L(0); PG8_BAR; PG8_MMA(0, 0, At, B0); PG8_MMA(0, 1, At, B1); PG8_BAR; PG8_SCHED;
	s_setprio 1
	s_waitcnt lgkmcnt(0)
	v_mfma_f32_16x16x32_bf16 v[62:65], v[142:145], v[192:195], v[62:65]
	v_mfma_f32_16x16x32_bf16 v[58:61], v[158:161], v[192:195], v[58:61]
	v_mfma_f32_16x16x32_bf16 v[46:49], v[142:145], v[200:203], v[46:49]
	v_mfma_f32_16x16x32_bf16 v[42:45], v[158:161], v[200:203], v[42:45]
	v_mfma_f32_16x16x32_bf16 v[30:33], v[142:145], v[208:211], v[30:33]
	v_mfma_f32_16x16x32_bf16 v[26:29], v[158:161], v[208:211], v[26:29]
	v_mfma_f32_16x16x32_bf16 v[14:17], v[142:145], v[216:219], v[14:17]
	v_mfma_f32_16x16x32_bf16 v[10:13], v[158:161], v[216:219], v[10:13]
	v_mfma_f32_16x16x32_bf16 v[62:65], v[154:157], v[196:199], v[62:65]
	v_mfma_f32_16x16x32_bf16 v[58:61], v[162:165], v[196:199], v[58:61]
	v_mfma_f32_16x16x32_bf16 v[46:49], v[154:157], v[204:207], v[46:49]
	v_mfma_f32_16x16x32_bf16 v[42:45], v[162:165], v[204:207], v[42:45]
	v_mfma_f32_16x16x32_bf16 v[30:33], v[154:157], v[212:215], v[30:33]
	v_mfma_f32_16x16x32_bf16 v[26:29], v[162:165], v[212:215], v[26:29]
	v_mfma_f32_16x16x32_bf16 v[14:17], v[154:157], v[220:223], v[14:17]
	v_mfma_f32_16x16x32_bf16 v[10:13], v[162:165], v[220:223], v[10:13]
	s_setprio 0
	s_setprio 1
	v_mfma_f32_16x16x32_bf16 v[54:57], v[166:169], v[192:195], v[54:57]
	v_mfma_f32_16x16x32_bf16 v[50:53], v[174:177], v[192:195], v[50:53]
	v_mfma_f32_16x16x32_bf16 v[38:41], v[166:169], v[200:203], v[38:41]
	v_mfma_f32_16x16x32_bf16 v[34:37], v[174:177], v[200:203], v[34:37]
	v_mfma_f32_16x16x32_bf16 v[22:25], v[166:169], v[208:211], v[22:25]
	v_mfma_f32_16x16x32_bf16 v[18:21], v[174:177], v[208:211], v[18:21]
	v_mfma_f32_16x16x32_bf16 v[6:9], v[166:169], v[216:219], v[6:9]
	v_mfma_f32_16x16x32_bf16 v[2:5], v[174:177], v[216:219], v[2:5]
	v_mfma_f32_16x16x32_bf16 v[54:57], v[170:173], v[196:199], v[54:57]
	v_mfma_f32_16x16x32_bf16 v[50:53], v[188:191], v[196:199], v[50:53]
	v_mfma_f32_16x16x32_bf16 v[38:41], v[170:173], v[204:207], v[38:41]
	v_mfma_f32_16x16x32_bf16 v[34:37], v[188:191], v[204:207], v[34:37]
	v_mfma_f32_16x16x32_bf16 v[22:25], v[170:173], v[212:215], v[22:25]
	v_mfma_f32_16x16x32_bf16 v[18:21], v[188:191], v[212:215], v[18:21]
	v_mfma_f32_16x16x32_bf16 v[6:9], v[170:173], v[220:223], v[6:9]
	v_mfma_f32_16x16x32_bf16 v[2:5], v[188:191], v[220:223], v[2:5]
	s_setprio 0
	s_barrier
	s_add_i32 s75, 0, 0x18000
	v_add_u32_e32 v148, s75, v150
	s_add_i32 s76, 0, 0x1c000
	ds_read_b128 v[142:145], v148
	ds_read_b128 v[154:157], v148 offset:1024
	ds_read_b128 v[158:161], v148 offset:2048
	ds_read_b128 v[162:165], v148 offset:3072
	v_add_u32_e32 v148, s76, v150
	ds_read_b128 v[166:169], v148
	ds_read_b128 v[170:173], v148 offset:1024
	ds_read_b128 v[174:177], v148 offset:2048
	ds_read_b128 v[188:191], v148 offset:3072
	s_add_u32 s40, s40, 0x40000
	s_addc_u32 s41, s41, 0
	s_mov_b32 m0, s49
	v_lshl_add_u64 v[226:227], s[40:41], 0, v[130:131]
	ds_read_b128 v[192:195], v152 offset:32768
	ds_read_b128 v[196:199], v152 offset:33792
	ds_read_b128 v[200:203], v152 offset:34816
	ds_read_b128 v[204:207], v152 offset:35840
	ds_read_b128 v[208:211], v152 offset:36864
	ds_read_b128 v[212:215], v152 offset:37888
	ds_read_b128 v[216:219], v152 offset:38912
	ds_read_b128 v[220:223], v152 offset:39936
	global_load_lds_dwordx4 v[226:227], off
	v_lshl_add_u64 v[226:227], s[40:41], 0, v[132:133]
	s_mov_b32 m0, s50
	s_nop 0
	global_load_lds_dwordx4 v[226:227], off
	s_waitcnt vmcnt(8)
	s_waitcnt lgkmcnt(0)
	s_barrier
	s_setprio 1
	s_waitcnt lgkmcnt(0)
	v_mfma_f32_16x16x32_bf16 v[126:129], v[142:145], v[192:195], v[126:129]
	v_mfma_f32_16x16x32_bf16 v[122:125], v[158:161], v[192:195], v[122:125]
	v_mfma_f32_16x16x32_bf16 v[110:113], v[142:145], v[200:203], v[110:113]
	v_mfma_f32_16x16x32_bf16 v[106:109], v[158:161], v[200:203], v[106:109]
	v_mfma_f32_16x16x32_bf16 v[94:97], v[142:145], v[208:211], v[94:97]
	v_mfma_f32_16x16x32_bf16 v[90:93], v[158:161], v[208:211], v[90:93]
	v_mfma_f32_16x16x32_bf16 v[78:81], v[142:145], v[216:219], v[78:81]
	v_mfma_f32_16x16x32_bf16 v[74:77], v[158:161], v[216:219], v[74:77]
	v_mfma_f32_16x16x32_bf16 v[126:129], v[154:157], v[196:199], v[126:129]
	v_mfma_f32_16x16x32_bf16 v[122:125], v[162:165], v[196:199], v[122:125]
	v_mfma_f32_16x16x32_bf16 v[110:113], v[154:157], v[204:207], v[110:113]
	v_mfma_f32_16x16x32_bf16 v[106:109], v[162:165], v[204:207], v[106:109]
	v_mfma_f32_16x16x32_bf16 v[94:97], v[154:157], v[212:215], v[94:97]
	v_mfma_f32_16x16x32_bf16 v[90:93], v[162:165], v[212:215], v[90:93]
	v_mfma_f32_16x16x32_bf16 v[78:81], v[154:157], v[220:223], v[78:81]
	v_mfma_f32_16x16x32_bf16 v[74:77], v[162:165], v[220:223], v[74:77]
	s_setprio 0
	s_setprio 1
	v_mfma_f32_16x16x32_bf16 v[118:121], v[166:169], v[192:195], v[118:121]
	v_mfma_f32_16x16x32_bf16 v[114:117], v[174:177], v[192:195], v[114:117]
	v_mfma_f32_16x16x32_bf16 v[102:105], v[166:169], v[200:203], v[102:105]
	v_mfma_f32_16x16x32_bf16 v[98:101], v[174:177], v[200:203], v[98:101]
	v_mfma_f32_16x16x32_bf16 v[86:89], v[166:169], v[208:211], v[86:89]
	v_mfma_f32_16x16x32_bf16 v[82:85], v[174:177], v[208:211], v[82:85]
	v_mfma_f32_16x16x32_bf16 v[70:73], v[166:169], v[216:219], v[70:73]
	v_mfma_f32_16x16x32_bf16 v[66:69], v[174:177], v[216:219], v[66:69]
	v_mfma_f32_16x16x32_bf16 v[118:121], v[170:173], v[196:199], v[118:121]
	v_mfma_f32_16x16x32_bf16 v[114:117], v[188:191], v[196:199], v[114:117]
	v_mfma_f32_16x16x32_bf16 v[102:105], v[170:173], v[204:207], v[102:105]
	v_mfma_f32_16x16x32_bf16 v[98:101], v[188:191], v[204:207], v[98:101]
	v_mfma_f32_16x16x32_bf16 v[86:89], v[170:173], v[212:215], v[86:89]
	v_mfma_f32_16x16x32_bf16 v[82:85], v[188:191], v[212:215], v[82:85]
	v_mfma_f32_16x16x32_bf16 v[70:73], v[170:173], v[220:223], v[70:73]
	v_mfma_f32_16x16x32_bf16 v[66:69], v[188:191], v[220:223], v[66:69]
	s_setprio 0
	s_barrier
; #define PG8_STAGE(bufoff, gbase, voff) do { _Pragma("unroll") for (int _i = 0; _i < 2; ++_i) \
;         __builtin_amdgcn_global_load_lds((const unsigned*)((const char*)(gbase) + (voff)[_i]), (PG8_LAS unsigned*)(lds + (bufoff) + ldsw + _i * 8192), 16, 0, 0); } while (0)
; #define PG8_LDA(dst, b, h) do { _Pragma("unroll") for (int m = 0; m < 4; ++m) _Pragma("unroll") for (int k = 0; k < 2; ++k) dst[m][k] = *(const PG8_LAS bf16x8*)(lds + PG8_SA(b, h) + aoff + m * 2048 + k * 1024); } while (0)
; #define PG8_MMA(ai, bj, At, Bt) do { __builtin_amdgcn_s_setprio(1); _Pragma("unroll") for (int m = 0; m < 4; ++m) _Pragma("unroll") for (int n = 0; n < 2; ++n) _Pragma("unroll") for (int k = 0; k < 2; ++k) \
;         acc[ai][bj][m][n] = __builtin_amdgcn_mfma_f32_16x16x32_bf16(Bt[n][k], At[m][k], acc[ai][bj][m][n], 0, 0, 0); __builtin_amdgcn_s_setprio(0); } while (0)
; #define PG8_WAIT_V(n) asm volatile("s_waitcnt vmcnt(" #n ")" ::: "memory")
; #define PG8_WAIT_L(n) asm volatile("s_waitcnt lgkmcnt(" #n ")" ::: "memory")
; #define PG8_BAR __builtin_amdgcn_s_barrier()
; #define PG8_SCHED __builtin_amdgcn_sched_barrier(0)
; template <class Epi, class Sched, bool ALIGN_EPI = false, bool SP2 = false>
; __device__ __forceinline__ void gemm_phase(PG8_LAS unsigned char* lds, const Gemm g, const Sched& S, const Epi& E) {
;     ...
;         for (int t = 0; t < nt; t += 2) {
;             const bool last = (t == nt - 2);
;             const char* a1 = cA + (size_t)(t + 1) * kstep;
;             const char* a2 = last ? nA : cA + (size_t)(t + 2) * kstep; const char* b2 = last ? nB : cB + (size_t)(t + 2) * kstep;
;             const char* a3 = a2 + kstep; const char* b3 = b2 + kstep;
;     ...
;             PG8_LDA(At, 1, 1); PG8_STAGE(PG8_SB(1, 0), b3, voffB); PG8_STAGE(PG8_SB(1, 1), b3 + hstep, voffB); PG8_STAGE(PG8_SA(1, 0), a3, voffA);
;             PG8_WAIT_V(8); PG8_WAIT_L(0); PG8_BAR; PG8_MMA(1, 0, At, B0); PG8_MMA(1, 1, At, B1); PG8_BAR; PG8_SCHED;
	s_add_i32 s40, s75, s47
	v_lshl_add_u64 v[146:147], v[146:147], 0, s[66:67]
	s_mov_b32 m0, s40
	ds_read_b128 v[192:195], v152 offset:49152
	ds_read_b128 v[196:199], v152 offset:50176
	ds_read_b128 v[200:203], v152 offset:51200
	ds_read_b128 v[204:207], v152 offset:52224
	ds_read_b128 v[208:211], v152 offset:53248
	ds_read_b128 v[212:215], v152 offset:54272
	ds_read_b128 v[216:219], v152 offset:55296
	ds_read_b128 v[220:223], v152 offset:56320
	global_load_lds_dwordx4 v[146:147], off
	s_add_i32 m0, s40, 0x2000
	s_add_u32 s38, s38, 0x40080
	v_lshl_add_u64 v[146:147], v[182:183], 0, s[66:67]
	s_addc_u32 s39, s39, 0
	s_add_i32 s40, s76, s47
	global_load_lds_dwordx4 v[146:147], off
	v_lshl_add_u64 v[146:147], s[38:39], 0, v[0:1]
	s_mov_b32 m0, s40
	s_nop 0
	global_load_lds_dwordx4 v[146:147], off
	v_lshl_add_u64 v[146:147], s[38:39], 0, v[134:135]
	s_add_i32 m0, s40, 0x2000
	s_nop 0
	global_load_lds_dwordx4 v[146:147], off
	v_lshl_add_u64 v[146:147], v[184:185], 0, s[66:67]
	s_mov_b32 m0, s68
	s_nop 0
	global_load_lds_dwordx4 v[146:147], off
	v_lshl_add_u64 v[146:147], v[224:225], 0, s[66:67]
	s_mov_b32 m0, s69
	s_nop 0
	global_load_lds_dwordx4 v[146:147], off
	s_waitcnt vmcnt(8)
	s_waitcnt lgkmcnt(0)
	s_barrier
	s_setprio 1
	s_waitcnt lgkmcnt(0)
	v_mfma_f32_16x16x32_bf16 v[62:65], v[142:145], v[192:195], v[62:65]
	v_mfma_f32_16x16x32_bf16 v[58:61], v[158:161], v[192:195], v[58:61]
	v_mfma_f32_16x16x32_bf16 v[46:49], v[142:145], v[200:203], v[46:49]
	v_mfma_f32_16x16x32_bf16 v[42:45], v[158:161], v[200:203], v[42:45]
	v_mfma_f32_16x16x32_bf16 v[30:33], v[142:145], v[208:211], v[30:33]
	v_mfma_f32_16x16x32_bf16 v[26:29], v[158:161], v[208:211], v[26:29]
	v_mfma_f32_16x16x32_bf16 v[14:17], v[142:145], v[216:219], v[14:17]
	v_mfma_f32_16x16x32_bf16 v[10:13], v[158:161], v[216:219], v[10:13]
	v_mfma_f32_16x16x32_bf16 v[62:65], v[154:157], v[196:199], v[62:65]
	v_mfma_f32_16x16x32_bf16 v[58:61], v[162:165], v[196:199], v[58:61]
	v_mfma_f32_16x16x32_bf16 v[46:49], v[154:157], v[204:207], v[46:49]
	v_mfma_f32_16x16x32_bf16 v[42:45], v[162:165], v[204:207], v[42:45]
	v_mfma_f32_16x16x32_bf16 v[30:33], v[154:157], v[212:215], v[30:33]
	v_mfma_f32_16x16x32_bf16 v[26:29], v[162:165], v[212:215], v[26:29]
	v_mfma_f32_16x16x32_bf16 v[14:17], v[154:157], v[220:223], v[14:17]
	v_mfma_f32_16x16x32_bf16 v[10:13], v[162:165], v[220:223], v[10:13]
	s_setprio 0
	s_setprio 1
	v_mfma_f32_16x16x32_bf16 v[54:57], v[166:169], v[192:195], v[54:57]
	v_mfma_f32_16x16x32_bf16 v[50:53], v[174:177], v[192:195], v[50:53]
	v_mfma_f32_16x16x32_bf16 v[38:41], v[166:169], v[200:203], v[38:41]
	v_mfma_f32_16x16x32_bf16 v[34:37], v[174:177], v[200:203], v[34:37]
	v_mfma_f32_16x16x32_bf16 v[22:25], v[166:169], v[208:211], v[22:25]
	v_mfma_f32_16x16x32_bf16 v[18:21], v[174:177], v[208:211], v[18:21]
	v_mfma_f32_16x16x32_bf16 v[6:9], v[166:169], v[216:219], v[6:9]
	v_mfma_f32_16x16x32_bf16 v[2:5], v[174:177], v[216:219], v[2:5]
	v_mfma_f32_16x16x32_bf16 v[54:57], v[170:173], v[196:199], v[54:57]
	v_mfma_f32_16x16x32_bf16 v[50:53], v[188:191], v[196:199], v[50:53]
	v_mfma_f32_16x16x32_bf16 v[38:41], v[170:173], v[204:207], v[38:41]
	v_mfma_f32_16x16x32_bf16 v[34:37], v[188:191], v[204:207], v[34:37]
	v_mfma_f32_16x16x32_bf16 v[22:25], v[170:173], v[212:215], v[22:25]
	v_mfma_f32_16x16x32_bf16 v[18:21], v[188:191], v[212:215], v[18:21]
	v_mfma_f32_16x16x32_bf16 v[6:9], v[170:173], v[220:223], v[6:9]
	v_mfma_f32_16x16x32_bf16 v[2:5], v[188:191], v[220:223], v[2:5]
	s_setprio 0
	s_add_i32 s74, s74, 2
	s_add_u32 s30, s30, 0x100
	s_addc_u32 s31, s31, 0
	s_add_u32 s72, s72, 0x100
	s_addc_u32 s73, s73, 0
	s_add_u32 s38, s30, 0xfffc0080
	s_addc_u32 s39, s31, -1
	s_add_i32 s75, 0, 0x10000
	s_cmp_eq_u32 s74, 12
	s_cselect_b32 s41, s5, s39
	s_cselect_b32 s40, s19, s38
	s_cselect_b32 s39, s17, s73
	s_cselect_b32 s38, s71, s72
	s_add_i32 s78, 0, 0x14000
	s_cmp_gt_u32 s74, 13
	s_barrier
	s_cbranch_scc0 .Lrot_ip
	s_and_b64 vcc, exec, s[12:13]
	s_cbranch_vccnz .LBB0_101
	v_lshl_add_u32 v142, s4, 8, v149
	s_cmp_gt_i32 s24, 11
	s_mov_b64 s[4:5], -1
	s_cbranch_scc1 .LBB0_102

; #define PG8_STAGE(bufoff, gbase, voff) do { _Pragma("unroll") for (int _i = 0; _i < 2; ++_i) \
;         __builtin_amdgcn_global_load_lds((const unsigned*)((const char*)(gbase) + (voff)[_i]), (PG8_LAS unsigned*)(lds + (bufoff) + ldsw + _i * 8192), 16, 0, 0); } while (0)
; #define PG8_LDA(dst, b, h) do { _Pragma("unroll") for (int m = 0; m < 4; ++m) _Pragma("unroll") for (int k = 0; k < 2; ++k) dst[m][k] = *(const PG8_LAS bf16x8*)(lds + PG8_SA(b, h) + aoff + m * 2048 + k * 1024); } while (0)
; #define PG8_LDB(dst, b, h) do { _Pragma("unroll") for (int n = 0; n < 2; ++n) _Pragma("unroll") for (int k = 0; k < 2; ++k) dst[n][k] = *(const PG8_LAS bf16x8*)(lds + PG8_SB(b, h) + boff + n * 2048 + k * 1024); } while (0)
; #define PG8_MMA(ai, bj, At, Bt) do { __builtin_amdgcn_s_setprio(1); _Pragma("unroll") for (int m = 0; m < 4; ++m) _Pragma("unroll") for (int n = 0; n < 2; ++n) _Pragma("unroll") for (int k = 0; k < 2; ++k) \
;         acc[ai][bj][m][n] = __builtin_amdgcn_mfma_f32_16x16x32_bf16(Bt[n][k], At[m][k], acc[ai][bj][m][n], 0, 0, 0); __builtin_amdgcn_s_setprio(0); } while (0)
; #define PG8_WAIT_V(n) asm volatile("s_waitcnt vmcnt(" #n ")" ::: "memory")
; #define PG8_WAIT_L(n) asm volatile("s_waitcnt lgkmcnt(" #n ")" ::: "memory")
; #define PG8_BAR __builtin_amdgcn_s_barrier()
; #define PG8_SCHED __builtin_amdgcn_sched_barrier(0)
; template <class Epi, class Sched, bool ALIGN_EPI = false, bool SP2 = false>
; __device__ __forceinline__ void gemm_phase(PG8_LAS unsigned char* lds, const Gemm g, const Sched& S, const Epi& E) {
;     ...
;             PG8_LDB(B0, 0, 0); PG8_LDB(B1, 0, 1); PG8_SCHED; PG8_LDA(At, 0, 0); PG8_STAGE(PG8_SA(1, 1), a1 + hstep, voffA);
;             PG8_WAIT_V(8); PG8_WAIT_L(0); PG8_BAR; PG8_MMA(0, 0, At, B0); PG8_MMA(0, 1, At, B1); PG8_BAR; PG8_SCHED;
;             PG8_LDA(At, 0, 1); PG8_STAGE(PG8_SB(0, 0), b2, voffB); PG8_STAGE(PG8_SB(0, 1), b2 + hstep, voffB); PG8_STAGE(PG8_SA(0, 0), a2, voffA);
;             PG8_WAIT_V(8); PG8_WAIT_L(0); PG8_BAR; PG8_MMA(1, 0, At, B0); PG8_MMA(1, 1, At, B1); PG8_BAR; PG8_SCHED;
.Lrot_op:
	v_add_u32_e32 v94, s84, v157
	v_add_u32_e32 v168, s85, v157
	ds_read_b128 v[82:85], v94
	ds_read_b128 v[86:89], v94 offset:1024
	ds_read_b128 v[90:93], v94 offset:2048
	ds_read_b128 v[94:97], v94 offset:3072
	ds_read_b128 v[152:155], v168
	ds_read_b128 v[160:163], v168 offset:1024
	ds_read_b128 v[164:167], v168 offset:2048
	ds_read_b128 v[168:171], v168 offset:3072
	v_lshl_add_u64 v[176:177], s[42:43], 0, v[148:149]
	s_add_i32 m0, s72, 0xc000
	ds_read_b128 v[172:175], v159
	ds_read_b128 v[182:185], v159 offset:1024
	ds_read_b128 v[188:191], v159 offset:2048
	ds_read_b128 v[192:195], v159 offset:3072
	ds_read_b128 v[196:199], v159 offset:4096
	ds_read_b128 v[200:203], v159 offset:5120
	ds_read_b128 v[204:207], v159 offset:6144
	ds_read_b128 v[208:211], v159 offset:7168
	global_load_lds_dwordx4 v[176:177], off
	v_lshl_add_u64 v[176:177], s[42:43], 0, v[150:151]
	s_add_i32 m0, s72, 0xe000
	s_nop 0
	global_load_lds_dwordx4 v[176:177], off
	s_waitcnt vmcnt(8)
	s_waitcnt lgkmcnt(0)
	s_barrier
	s_setprio 1
	s_waitcnt lgkmcnt(0)
	v_mfma_f32_16x16x32_bf16 v[142:145], v[82:85], v[172:175], v[142:145]
	v_mfma_f32_16x16x32_bf16 v[138:141], v[90:93], v[172:175], v[138:141]
	v_mfma_f32_16x16x32_bf16 v[126:129], v[82:85], v[188:191], v[126:129]
	v_mfma_f32_16x16x32_bf16 v[122:125], v[90:93], v[188:191], v[122:125]
	v_mfma_f32_16x16x32_bf16 v[110:113], v[82:85], v[196:199], v[110:113]
	v_mfma_f32_16x16x32_bf16 v[106:109], v[90:93], v[196:199], v[106:109]
	v_mfma_f32_16x16x32_bf16 v[78:81], v[82:85], v[204:207], v[78:81]
	v_mfma_f32_16x16x32_bf16 v[74:77], v[90:93], v[204:207], v[74:77]
	v_mfma_f32_16x16x32_bf16 v[142:145], v[86:89], v[182:185], v[142:145]
	v_mfma_f32_16x16x32_bf16 v[138:141], v[94:97], v[182:185], v[138:141]
	v_mfma_f32_16x16x32_bf16 v[126:129], v[86:89], v[192:195], v[126:129]
	v_mfma_f32_16x16x32_bf16 v[122:125], v[94:97], v[192:195], v[122:125]
	v_mfma_f32_16x16x32_bf16 v[110:113], v[86:89], v[200:203], v[110:113]
	v_mfma_f32_16x16x32_bf16 v[106:109], v[94:97], v[200:203], v[106:109]
	v_mfma_f32_16x16x32_bf16 v[78:81], v[86:89], v[208:211], v[78:81]
	v_mfma_f32_16x16x32_bf16 v[74:77], v[94:97], v[208:211], v[74:77]
	s_setprio 0
	s_setprio 1
	v_mfma_f32_16x16x32_bf16 v[134:137], v[152:155], v[172:175], v[134:137]
	v_mfma_f32_16x16x32_bf16 v[130:133], v[164:167], v[172:175], v[130:133]
	v_mfma_f32_16x16x32_bf16 v[118:121], v[152:155], v[188:191], v[118:121]
	v_mfma_f32_16x16x32_bf16 v[114:117], v[164:167], v[188:191], v[114:117]
	v_mfma_f32_16x16x32_bf16 v[102:105], v[152:155], v[196:199], v[102:105]
	v_mfma_f32_16x16x32_bf16 v[98:101], v[164:167], v[196:199], v[98:101]
	v_mfma_f32_16x16x32_bf16 v[70:73], v[152:155], v[204:207], v[70:73]
	v_mfma_f32_16x16x32_bf16 v[66:69], v[164:167], v[204:207], v[66:69]
	v_mfma_f32_16x16x32_bf16 v[134:137], v[160:163], v[182:185], v[134:137]
	v_mfma_f32_16x16x32_bf16 v[130:133], v[168:171], v[182:185], v[130:133]
	v_mfma_f32_16x16x32_bf16 v[118:121], v[160:163], v[192:195], v[118:121]
	v_mfma_f32_16x16x32_bf16 v[114:117], v[168:171], v[192:195], v[114:117]
	v_mfma_f32_16x16x32_bf16 v[102:105], v[160:163], v[200:203], v[102:105]
	v_mfma_f32_16x16x32_bf16 v[98:101], v[168:171], v[200:203], v[98:101]
	v_mfma_f32_16x16x32_bf16 v[70:73], v[160:163], v[208:211], v[70:73]
	v_mfma_f32_16x16x32_bf16 v[66:69], v[168:171], v[208:211], v[66:69]
	s_setprio 0
	s_barrier
	s_add_i32 s42, s84, s71
	v_lshl_add_u64 v[176:177], s[46:47], 0, v[0:1]
	s_mov_b32 m0, s42
	ds_read_b128 v[172:175], v159 offset:16384
	ds_read_b128 v[182:185], v159 offset:17408
	ds_read_b128 v[188:191], v159 offset:18432
	ds_read_b128 v[192:195], v159 offset:19456
	ds_read_b128 v[196:199], v159 offset:20480
	ds_read_b128 v[200:203], v159 offset:21504
	ds_read_b128 v[204:207], v159 offset:22528
	ds_read_b128 v[208:211], v159 offset:23552
	global_load_lds_dwordx4 v[176:177], off
	s_add_i32 m0, s42, 0x2000
	s_add_u32 s42, s46, 0x40000
	v_lshl_add_u64 v[212:213], s[46:47], 0, v[146:147]
	s_addc_u32 s43, s47, 0
	s_add_i32 s84, s85, s71
	global_load_lds_dwordx4 v[212:213], off
	v_lshl_add_u64 v[214:215], s[42:43], 0, v[0:1]
	s_mov_b32 m0, s84
	v_lshl_add_u64 v[216:217], s[48:49], 0, v[146:147]
	global_load_lds_dwordx4 v[214:215], off
	v_lshl_add_u64 v[214:215], s[42:43], 0, v[146:147]
	s_add_i32 m0, s84, 0x2000
	s_nop 0
	global_load_lds_dwordx4 v[214:215], off
	v_lshl_add_u64 v[214:215], s[48:49], 0, v[0:1]
	s_mov_b32 m0, s72
	s_nop 0
	global_load_lds_dwordx4 v[214:215], off
	s_mov_b32 m0, s73
	s_nop 0
	global_load_lds_dwordx4 v[216:217], off
	s_waitcnt vmcnt(8)
	s_waitcnt lgkmcnt(0)
	s_barrier
; #define PG8_STAGE(bufoff, gbase, voff) do { _Pragma("unroll") for (int _i = 0; _i < 2; ++_i) \
;         __builtin_amdgcn_global_load_lds((const unsigned*)((const char*)(gbase) + (voff)[_i]), (PG8_LAS unsigned*)(lds + (bufoff) + ldsw + _i * 8192), 16, 0, 0); } while (0)
; #define PG8_LDA(dst, b, h) do { _Pragma("unroll") for (int m = 0; m < 4; ++m) _Pragma("unroll") for (int k = 0; k < 2; ++k) dst[m][k] = *(const PG8_LAS bf16x8*)(lds + PG8_SA(b, h) + aoff + m * 2048 + k * 1024); } while (0)
; #define PG8_LDB(dst, b, h) do { _Pragma("unroll") for (int n = 0; n < 2; ++n) _Pragma("unroll") for (int k = 0; k < 2; ++k) dst[n][k] = *(const PG8_LAS bf16x8*)(lds + PG8_SB(b, h) + boff + n * 2048 + k * 1024); } while (0)
; #define PG8_MMA(ai, bj, At, Bt) do { __builtin_amdgcn_s_setprio(1); _Pragma("unroll") for (int m = 0; m < 4; ++m) _Pragma("unroll") for (int n = 0; n < 2; ++n) _Pragma("unroll") for (int k = 0; k < 2; ++k) \
;         acc[ai][bj][m][n] = __builtin_amdgcn_mfma_f32_16x16x32_bf16(Bt[n][k], At[m][k], acc[ai][bj][m][n], 0, 0, 0); __builtin_amdgcn_s_setprio(0); } while (0)
; #define PG8_WAIT_V(n) asm volatile("s_waitcnt vmcnt(" #n ")" ::: "memory")
; #define PG8_WAIT_L(n) asm volatile("s_waitcnt lgkmcnt(" #n ")" ::: "memory")
; #define PG8_BAR __builtin_amdgcn_s_barrier()
; #define PG8_SCHED __builtin_amdgcn_sched_barrier(0)
; template <class Epi, class Sched, bool ALIGN_EPI = false, bool SP2 = false>
; __device__ __forceinline__ void gemm_phase(PG8_LAS unsigned char* lds, const Gemm g, const Sched& S, const Epi& E) {
;     ...
;             PG8_WAIT_V(8); PG8_WAIT_L(0); PG8_BAR; PG8_MMA(1, 0, At, B0); PG8_MMA(1, 1, At, B1); PG8_BAR; PG8_SCHED;
;             PG8_LDB(B0, 1, 0); PG8_LDB(B1, 1, 1); PG8_SCHED; PG8_LDA(At, 1, 0); PG8_STAGE(PG8_SA(0, 1), a2 + hstep, voffA);
;             PG8_WAIT_V(8); PG8_WAIT_L(0); PG8_BAR; PG8_MMA(0, 0, At, B0); PG8_MMA(0, 1, At, B1); PG8_BAR; PG8_SCHED;
	s_setprio 1
	s_waitcnt lgkmcnt(0)
	v_mfma_f32_16x16x32_bf16 v[62:65], v[82:85], v[172:175], v[62:65]
	v_mfma_f32_16x16x32_bf16 v[58:61], v[90:93], v[172:175], v[58:61]
	v_mfma_f32_16x16x32_bf16 v[46:49], v[82:85], v[188:191], v[46:49]
	v_mfma_f32_16x16x32_bf16 v[42:45], v[90:93], v[188:191], v[42:45]
	v_mfma_f32_16x16x32_bf16 v[30:33], v[82:85], v[196:199], v[30:33]
	v_mfma_f32_16x16x32_bf16 v[26:29], v[90:93], v[196:199], v[26:29]
	v_mfma_f32_16x16x32_bf16 v[14:17], v[82:85], v[204:207], v[14:17]
	v_mfma_f32_16x16x32_bf16 v[10:13], v[90:93], v[204:207], v[10:13]
	v_mfma_f32_16x16x32_bf16 v[62:65], v[86:89], v[182:185], v[62:65]
	v_mfma_f32_16x16x32_bf16 v[58:61], v[94:97], v[182:185], v[58:61]
	v_mfma_f32_16x16x32_bf16 v[46:49], v[86:89], v[192:195], v[46:49]
	v_mfma_f32_16x16x32_bf16 v[42:45], v[94:97], v[192:195], v[42:45]
	v_mfma_f32_16x16x32_bf16 v[30:33], v[86:89], v[200:203], v[30:33]
	v_mfma_f32_16x16x32_bf16 v[26:29], v[94:97], v[200:203], v[26:29]
	v_mfma_f32_16x16x32_bf16 v[14:17], v[86:89], v[208:211], v[14:17]
	v_mfma_f32_16x16x32_bf16 v[10:13], v[94:97], v[208:211], v[10:13]
	s_setprio 0
	s_setprio 1
	v_mfma_f32_16x16x32_bf16 v[54:57], v[152:155], v[172:175], v[54:57]
	v_mfma_f32_16x16x32_bf16 v[50:53], v[164:167], v[172:175], v[50:53]
	v_mfma_f32_16x16x32_bf16 v[38:41], v[152:155], v[188:191], v[38:41]
	v_mfma_f32_16x16x32_bf16 v[34:37], v[164:167], v[188:191], v[34:37]
	v_mfma_f32_16x16x32_bf16 v[22:25], v[152:155], v[196:199], v[22:25]
	v_mfma_f32_16x16x32_bf16 v[18:21], v[164:167], v[196:199], v[18:21]
	v_mfma_f32_16x16x32_bf16 v[6:9], v[152:155], v[204:207], v[6:9]
	v_mfma_f32_16x16x32_bf16 v[2:5], v[164:167], v[204:207], v[2:5]
	v_mfma_f32_16x16x32_bf16 v[54:57], v[160:163], v[182:185], v[54:57]
	v_mfma_f32_16x16x32_bf16 v[50:53], v[168:171], v[182:185], v[50:53]
	v_mfma_f32_16x16x32_bf16 v[38:41], v[160:163], v[192:195], v[38:41]
	v_mfma_f32_16x16x32_bf16 v[34:37], v[168:171], v[192:195], v[34:37]
	v_mfma_f32_16x16x32_bf16 v[22:25], v[160:163], v[200:203], v[22:25]
	v_mfma_f32_16x16x32_bf16 v[18:21], v[168:171], v[200:203], v[18:21]
	v_mfma_f32_16x16x32_bf16 v[6:9], v[160:163], v[208:211], v[6:9]
	v_mfma_f32_16x16x32_bf16 v[2:5], v[168:171], v[208:211], v[2:5]
	s_setprio 0
	s_barrier
	s_add_i32 s84, 0, 0x18000
	s_add_i32 s85, 0, 0x1c000
	v_add_u32_e32 v94, s84, v157
	v_add_u32_e32 v168, s85, v157
	ds_read_b128 v[82:85], v94
	ds_read_b128 v[86:89], v94 offset:1024
	ds_read_b128 v[90:93], v94 offset:2048
	ds_read_b128 v[94:97], v94 offset:3072
	ds_read_b128 v[152:155], v168
	ds_read_b128 v[160:163], v168 offset:1024
	ds_read_b128 v[164:167], v168 offset:2048
	ds_read_b128 v[168:171], v168 offset:3072
	s_add_u32 s42, s48, 0x40000
	s_addc_u32 s43, s49, 0
	s_mov_b32 m0, s74
	v_lshl_add_u64 v[218:219], s[42:43], 0, v[0:1]
	ds_read_b128 v[172:175], v159 offset:32768
	ds_read_b128 v[182:185], v159 offset:33792
	ds_read_b128 v[188:191], v159 offset:34816
	ds_read_b128 v[192:195], v159 offset:35840
	ds_read_b128 v[196:199], v159 offset:36864
	ds_read_b128 v[200:203], v159 offset:37888
	ds_read_b128 v[204:207], v159 offset:38912
	ds_read_b128 v[208:211], v159 offset:39936
	global_load_lds_dwordx4 v[218:219], off
	v_lshl_add_u64 v[218:219], s[42:43], 0, v[146:147]
	s_mov_b32 m0, s75
	s_nop 0
	global_load_lds_dwordx4 v[218:219], off
	s_waitcnt vmcnt(8)
	s_waitcnt lgkmcnt(0)
	s_barrier
	s_setprio 1
	s_waitcnt lgkmcnt(0)
	v_mfma_f32_16x16x32_bf16 v[142:145], v[82:85], v[172:175], v[142:145]
	v_mfma_f32_16x16x32_bf16 v[138:141], v[90:93], v[172:175], v[138:141]
	v_mfma_f32_16x16x32_bf16 v[126:129], v[82:85], v[188:191], v[126:129]
	v_mfma_f32_16x16x32_bf16 v[122:125], v[90:93], v[188:191], v[122:125]
	v_mfma_f32_16x16x32_bf16 v[110:113], v[82:85], v[196:199], v[110:113]
	v_mfma_f32_16x16x32_bf16 v[106:109], v[90:93], v[196:199], v[106:109]
	v_mfma_f32_16x16x32_bf16 v[78:81], v[82:85], v[204:207], v[78:81]
	v_mfma_f32_16x16x32_bf16 v[74:77], v[90:93], v[204:207], v[74:77]
	v_mfma_f32_16x16x32_bf16 v[142:145], v[86:89], v[182:185], v[142:145]
	v_mfma_f32_16x16x32_bf16 v[138:141], v[94:97], v[182:185], v[138:141]
	v_mfma_f32_16x16x32_bf16 v[126:129], v[86:89], v[192:195], v[126:129]
	v_mfma_f32_16x16x32_bf16 v[122:125], v[94:97], v[192:195], v[122:125]
	v_mfma_f32_16x16x32_bf16 v[110:113], v[86:89], v[200:203], v[110:113]
	v_mfma_f32_16x16x32_bf16 v[106:109], v[94:97], v[200:203], v[106:109]
	v_mfma_f32_16x16x32_bf16 v[78:81], v[86:89], v[208:211], v[78:81]
	v_mfma_f32_16x16x32_bf16 v[74:77], v[94:97], v[208:211], v[74:77]
	s_setprio 0
	s_setprio 1
	v_mfma_f32_16x16x32_bf16 v[134:137], v[152:155], v[172:175], v[134:137]
	v_mfma_f32_16x16x32_bf16 v[130:133], v[164:167], v[172:175], v[130:133]
	v_mfma_f32_16x16x32_bf16 v[118:121], v[152:155], v[188:191], v[118:121]
	v_mfma_f32_16x16x32_bf16 v[114:117], v[164:167], v[188:191], v[114:117]
	v_mfma_f32_16x16x32_bf16 v[102:105], v[152:155], v[196:199], v[102:105]
	v_mfma_f32_16x16x32_bf16 v[98:101], v[164:167], v[196:199], v[98:101]
	v_mfma_f32_16x16x32_bf16 v[70:73], v[152:155], v[204:207], v[70:73]
	v_mfma_f32_16x16x32_bf16 v[66:69], v[164:167], v[204:207], v[66:69]
	v_mfma_f32_16x16x32_bf16 v[134:137], v[160:163], v[182:185], v[134:137]
	v_mfma_f32_16x16x32_bf16 v[130:133], v[168:171], v[182:185], v[130:133]
	v_mfma_f32_16x16x32_bf16 v[118:121], v[160:163], v[192:195], v[118:121]
	v_mfma_f32_16x16x32_bf16 v[114:117], v[168:171], v[192:195], v[114:117]
	v_mfma_f32_16x16x32_bf16 v[102:105], v[160:163], v[200:203], v[102:105]
	v_mfma_f32_16x16x32_bf16 v[98:101], v[168:171], v[200:203], v[98:101]
	v_mfma_f32_16x16x32_bf16 v[70:73], v[160:163], v[208:211], v[70:73]
	v_mfma_f32_16x16x32_bf16 v[66:69], v[168:171], v[208:211], v[66:69]
	s_setprio 0
	s_barrier
; #define PG8_STAGE(bufoff, gbase, voff) do { _Pragma("unroll") for (int _i = 0; _i < 2; ++_i) \
;         __builtin_amdgcn_global_load_lds((const unsigned*)((const char*)(gbase) + (voff)[_i]), (PG8_LAS unsigned*)(lds + (bufoff) + ldsw + _i * 8192), 16, 0, 0); } while (0)
; #define PG8_LDA(dst, b, h) do { _Pragma("unroll") for (int m = 0; m < 4; ++m) _Pragma("unroll") for (int k = 0; k < 2; ++k) dst[m][k] = *(const PG8_LAS bf16x8*)(lds + PG8_SA(b, h) + aoff + m * 2048 + k * 1024); } while (0)
; #define PG8_MMA(ai, bj, At, Bt) do { __builtin_amdgcn_s_setprio(1); _Pragma("unroll") for (int m = 0; m < 4; ++m) _Pragma("unroll") for (int n = 0; n < 2; ++n) _Pragma("unroll") for (int k = 0; k < 2; ++k) \
;         acc[ai][bj][m][n] = __builtin_amdgcn_mfma_f32_16x16x32_bf16(Bt[n][k], At[m][k], acc[ai][bj][m][n], 0, 0, 0); __builtin_amdgcn_s_setprio(0); } while (0)
; #define PG8_WAIT_V(n) asm volatile("s_waitcnt vmcnt(" #n ")" ::: "memory")
; #define PG8_WAIT_L(n) asm volatile("s_waitcnt lgkmcnt(" #n ")" ::: "memory")
; #define PG8_BAR __builtin_amdgcn_s_barrier()
; #define PG8_SCHED __builtin_amdgcn_sched_barrier(0)
; template <class Epi, class Sched, bool ALIGN_EPI = false, bool SP2 = false>
; __device__ __forceinline__ void gemm_phase(PG8_LAS unsigned char* lds, const Gemm g, const Sched& S, const Epi& E) {
;     ...
;         for (int t = 0; t < nt; t += 2) {
;             const bool last = (t == nt - 2);
;             const char* a1 = cA + (size_t)(t + 1) * kstep;
;             const char* a2 = last ? nA : cA + (size_t)(t + 2) * kstep; const char* b2 = last ? nB : cB + (size_t)(t + 2) * kstep;
;             const char* a3 = a2 + kstep; const char* b3 = b2 + kstep;
;     ...
;             PG8_LDA(At, 1, 1); PG8_STAGE(PG8_SB(1, 0), b3, voffB); PG8_STAGE(PG8_SB(1, 1), b3 + hstep, voffB); PG8_STAGE(PG8_SA(1, 0), a3, voffA);
;             PG8_WAIT_V(8); PG8_WAIT_L(0); PG8_BAR; PG8_MMA(1, 0, At, B0); PG8_MMA(1, 1, At, B1); PG8_BAR; PG8_SCHED;
	s_add_i32 s42, s84, s71
	v_lshl_add_u64 v[176:177], v[176:177], 0, s[66:67]
	s_mov_b32 m0, s42
	ds_read_b128 v[172:175], v159 offset:49152
	ds_read_b128 v[182:185], v159 offset:50176
	ds_read_b128 v[188:191], v159 offset:51200
	ds_read_b128 v[192:195], v159 offset:52224
	ds_read_b128 v[196:199], v159 offset:53248
	ds_read_b128 v[200:203], v159 offset:54272
	ds_read_b128 v[204:207], v159 offset:55296
	ds_read_b128 v[208:211], v159 offset:56320
	global_load_lds_dwordx4 v[176:177], off
	s_add_i32 m0, s42, 0x2000
	s_add_u32 s42, s46, 0x40080
	v_lshl_add_u64 v[176:177], v[212:213], 0, s[66:67]
	s_addc_u32 s43, s47, 0
	s_add_i32 s46, s85, s71
	global_load_lds_dwordx4 v[176:177], off
	v_lshl_add_u64 v[176:177], s[42:43], 0, v[0:1]
	s_mov_b32 m0, s46
	s_nop 0
	global_load_lds_dwordx4 v[176:177], off
	v_lshl_add_u64 v[176:177], s[42:43], 0, v[146:147]
	s_add_i32 m0, s46, 0x2000
	s_nop 0
	global_load_lds_dwordx4 v[176:177], off
	v_lshl_add_u64 v[176:177], v[214:215], 0, s[66:67]
	s_mov_b32 m0, s77
	s_nop 0
	global_load_lds_dwordx4 v[176:177], off
	v_lshl_add_u64 v[176:177], v[216:217], 0, s[66:67]
	s_mov_b32 m0, s78
	s_nop 0
	global_load_lds_dwordx4 v[176:177], off
	s_waitcnt vmcnt(8)
	s_waitcnt lgkmcnt(0)
	s_barrier
	s_setprio 1
	s_waitcnt lgkmcnt(0)
	v_mfma_f32_16x16x32_bf16 v[62:65], v[82:85], v[172:175], v[62:65]
	v_mfma_f32_16x16x32_bf16 v[58:61], v[90:93], v[172:175], v[58:61]
	v_mfma_f32_16x16x32_bf16 v[46:49], v[82:85], v[188:191], v[46:49]
	v_mfma_f32_16x16x32_bf16 v[42:45], v[90:93], v[188:191], v[42:45]
	v_mfma_f32_16x16x32_bf16 v[30:33], v[82:85], v[196:199], v[30:33]
	v_mfma_f32_16x16x32_bf16 v[26:29], v[90:93], v[196:199], v[26:29]
	v_mfma_f32_16x16x32_bf16 v[14:17], v[82:85], v[204:207], v[14:17]
	v_mfma_f32_16x16x32_bf16 v[10:13], v[90:93], v[204:207], v[10:13]
	v_mfma_f32_16x16x32_bf16 v[62:65], v[86:89], v[182:185], v[62:65]
	v_mfma_f32_16x16x32_bf16 v[58:61], v[94:97], v[182:185], v[58:61]
	v_mfma_f32_16x16x32_bf16 v[46:49], v[86:89], v[192:195], v[46:49]
	v_mfma_f32_16x16x32_bf16 v[42:45], v[94:97], v[192:195], v[42:45]
	v_mfma_f32_16x16x32_bf16 v[30:33], v[86:89], v[200:203], v[30:33]
	v_mfma_f32_16x16x32_bf16 v[26:29], v[94:97], v[200:203], v[26:29]
	v_mfma_f32_16x16x32_bf16 v[14:17], v[86:89], v[208:211], v[14:17]
	v_mfma_f32_16x16x32_bf16 v[10:13], v[94:97], v[208:211], v[10:13]
	s_setprio 0
	s_setprio 1
	v_mfma_f32_16x16x32_bf16 v[54:57], v[152:155], v[172:175], v[54:57]
	v_mfma_f32_16x16x32_bf16 v[50:53], v[164:167], v[172:175], v[50:53]
	v_mfma_f32_16x16x32_bf16 v[38:41], v[152:155], v[188:191], v[38:41]
	v_mfma_f32_16x16x32_bf16 v[34:37], v[164:167], v[188:191], v[34:37]
	v_mfma_f32_16x16x32_bf16 v[22:25], v[152:155], v[196:199], v[22:25]
	v_mfma_f32_16x16x32_bf16 v[18:21], v[164:167], v[196:199], v[18:21]
	v_mfma_f32_16x16x32_bf16 v[6:9], v[152:155], v[204:207], v[6:9]
	v_mfma_f32_16x16x32_bf16 v[2:5], v[164:167], v[204:207], v[2:5]
	v_mfma_f32_16x16x32_bf16 v[54:57], v[160:163], v[182:185], v[54:57]
	v_mfma_f32_16x16x32_bf16 v[50:53], v[168:171], v[182:185], v[50:53]
	v_mfma_f32_16x16x32_bf16 v[38:41], v[160:163], v[192:195], v[38:41]
	v_mfma_f32_16x16x32_bf16 v[34:37], v[168:171], v[192:195], v[34:37]
	v_mfma_f32_16x16x32_bf16 v[22:25], v[160:163], v[200:203], v[22:25]
	v_mfma_f32_16x16x32_bf16 v[18:21], v[168:171], v[200:203], v[18:21]
	v_mfma_f32_16x16x32_bf16 v[6:9], v[160:163], v[208:211], v[6:9]
	v_mfma_f32_16x16x32_bf16 v[2:5], v[168:171], v[208:211], v[2:5]
	s_setprio 0
	s_add_i32 s83, s83, 2
	s_add_u32 s41, s41, 0x100
	s_addc_u32 s82, s82, 0
	s_mov_b64 s[42:43], s[44:45]
	s_add_u32 s44, s42, 0x100
	s_addc_u32 s45, s43, 0
	s_add_i32 s84, 0, 0x10000
	s_cmp_eq_u32 s83, 12
	s_cselect_b32 s49, s23, s45
	s_cselect_b32 s48, s26, s44
	s_cselect_b32 s47, s21, s82
	s_cselect_b32 s46, s39, s41
	s_add_i32 s85, 0, 0x14000
	s_cmp_gt_u32 s83, 13
	s_barrier
	s_cbranch_scc0 .Lrot_op
	s_and_b64 vcc, exec, s[18:19]
	s_cbranch_vccz .LBB0_885
	s_barrier

; #define PG8_STAGE(bufoff, gbase, voff) do { _Pragma("unroll") for (int _i = 0; _i < 2; ++_i) \
;         __builtin_amdgcn_global_load_lds((const unsigned*)((const char*)(gbase) + (voff)[_i]), (PG8_LAS unsigned*)(lds + (bufoff) + ldsw + _i * 8192), 16, 0, 0); } while (0)
; #define PG8_LDA(dst, b, h) do { _Pragma("unroll") for (int m = 0; m < 4; ++m) _Pragma("unroll") for (int k = 0; k < 2; ++k) dst[m][k] = *(const PG8_LAS bf16x8*)(lds + PG8_SA(b, h) + aoff + m * 2048 + k * 1024); } while (0)
; #define PG8_LDB(dst, b, h) do { _Pragma("unroll") for (int n = 0; n < 2; ++n) _Pragma("unroll") for (int k = 0; k < 2; ++k) dst[n][k] = *(const PG8_LAS bf16x8*)(lds + PG8_SB(b, h) + boff + n * 2048 + k * 1024); } while (0)
; #define PG8_MMA(ai, bj, At, Bt) do { __builtin_amdgcn_s_setprio(1); _Pragma("unroll") for (int m = 0; m < 4; ++m) _Pragma("unroll") for (int n = 0; n < 2; ++n) _Pragma("unroll") for (int k = 0; k < 2; ++k) \
;         acc[ai][bj][m][n] = __builtin_amdgcn_mfma_f32_16x16x32_bf16(Bt[n][k], At[m][k], acc[ai][bj][m][n], 0, 0, 0); __builtin_amdgcn_s_setprio(0); } while (0)
; #define PG8_WAIT_V(n) asm volatile("s_waitcnt vmcnt(" #n ")" ::: "memory")
; #define PG8_BAR __builtin_amdgcn_s_barrier()
; template <class Epi, class Sched, bool ALIGN_EPI = false, bool SP2 = false>
; __device__ __forceinline__ void gemm_phase(PG8_LAS unsigned char* lds, const Gemm g, const Sched& S, const Epi& E) {
;     ...
;         for (int t = 0; t < nt; t += 2) {
;             const bool last = (t == nt - 2);
;             const char* a1 = cA + (size_t)(t + 1) * kstep;
;             const char* a2 = last ? nA : cA + (size_t)(t + 2) * kstep; const char* b2 = last ? nB : cB + (size_t)(t + 2) * kstep;
;             const char* a3 = a2 + kstep; const char* b3 = b2 + kstep;
;             if (last && has_next) S.a_ready(nxt);
;             if constexpr (SP2) {
;             PG8_LDB(B0, 0, 0); PG8_LDB(B1, 0, 1); PG8_SCHED; PG8_LDA(At, 0, 0); PG8_STAGE(PG8_SA(1, 1), a1 + hstep, voffA);
;             PG8_WAIT_V(8); PG8_WAIT_L(0); PG8_BAR; PG8_MMA(0, 0, At, B0); PG8_MMA(0, 1, At, B1); PG8_BAR; PG8_SCHED;
;             PG8_LDA(At, 0, 1); PG8_STAGE(PG8_SB(0, 0), b2, voffB); PG8_STAGE(PG8_SB(0, 1), b2 + hstep, voffB); PG8_STAGE(PG8_SA(0, 0), a2, voffA);
;             PG8_WAIT_V(8); PG8_WAIT_L(0); PG8_BAR; PG8_MMA(1, 0, At, B0); PG8_MMA(1, 1, At, B1); PG8_BAR; PG8_SCHED;
.LBB0_966:
	s_add_u32 s24, s22, 0xfffc0080
	s_addc_u32 s25, s23, -1
	s_add_i32 s73, 0, 0x10000
	s_cmp_eq_u32 s72, 12
	s_cselect_b32 s31, s15, s25
	s_cselect_b32 s30, s68, s24
	s_cselect_b32 s25, s13, s71
	s_cselect_b32 s24, s69, s70
	s_add_i32 s76, 0, 0x14000
.Lrot_fu:
	v_add_u32_e32 v144, s73, v148
	ds_read_b128 v[140:143], v144
	ds_read_b128 v[152:155], v144 offset:1024
	ds_read_b128 v[156:159], v144 offset:2048
	ds_read_b128 v[160:163], v144 offset:3072
	v_add_u32_e32 v144, s76, v148
	ds_read_b128 v[164:167], v144
	ds_read_b128 v[168:171], v144 offset:1024
	ds_read_b128 v[172:175], v144 offset:2048
	ds_read_b128 v[182:185], v144 offset:3072
	v_lshl_add_u64 v[144:145], s[22:23], 0, v[136:137]
	s_add_i32 m0, s44, 0xc000
	ds_read_b128 v[188:191], v150
	ds_read_b128 v[192:195], v150 offset:1024
	ds_read_b128 v[196:199], v150 offset:2048
	ds_read_b128 v[200:203], v150 offset:3072
	ds_read_b128 v[204:207], v150 offset:4096
	ds_read_b128 v[208:211], v150 offset:5120
	ds_read_b128 v[212:215], v150 offset:6144
	ds_read_b128 v[216:219], v150 offset:7168
	global_load_lds_dwordx4 v[144:145], off
	v_lshl_add_u64 v[144:145], s[22:23], 0, v[138:139]
	s_add_i32 m0, s44, 0xe000
	s_nop 0
	global_load_lds_dwordx4 v[144:145], off
	s_waitcnt vmcnt(8)
	s_waitcnt lgkmcnt(0)
	s_barrier
	s_setprio 1
	s_waitcnt lgkmcnt(0)
	v_mfma_f32_16x16x32_bf16 v[126:129], v[140:143], v[188:191], v[126:129]
	v_mfma_f32_16x16x32_bf16 v[122:125], v[156:159], v[188:191], v[122:125]
	v_mfma_f32_16x16x32_bf16 v[110:113], v[140:143], v[196:199], v[110:113]
	v_mfma_f32_16x16x32_bf16 v[106:109], v[156:159], v[196:199], v[106:109]
	v_mfma_f32_16x16x32_bf16 v[94:97], v[140:143], v[204:207], v[94:97]
	v_mfma_f32_16x16x32_bf16 v[90:93], v[156:159], v[204:207], v[90:93]
	v_mfma_f32_16x16x32_bf16 v[78:81], v[140:143], v[212:215], v[78:81]
	v_mfma_f32_16x16x32_bf16 v[74:77], v[156:159], v[212:215], v[74:77]
	v_mfma_f32_16x16x32_bf16 v[126:129], v[152:155], v[192:195], v[126:129]
	v_mfma_f32_16x16x32_bf16 v[122:125], v[160:163], v[192:195], v[122:125]
	v_mfma_f32_16x16x32_bf16 v[110:113], v[152:155], v[200:203], v[110:113]
	v_mfma_f32_16x16x32_bf16 v[106:109], v[160:163], v[200:203], v[106:109]
	v_mfma_f32_16x16x32_bf16 v[94:97], v[152:155], v[208:211], v[94:97]
	v_mfma_f32_16x16x32_bf16 v[90:93], v[160:163], v[208:211], v[90:93]
	v_mfma_f32_16x16x32_bf16 v[78:81], v[152:155], v[216:219], v[78:81]
	v_mfma_f32_16x16x32_bf16 v[74:77], v[160:163], v[216:219], v[74:77]
	s_setprio 0
	s_setprio 1
	v_mfma_f32_16x16x32_bf16 v[118:121], v[164:167], v[188:191], v[118:121]
	v_mfma_f32_16x16x32_bf16 v[114:117], v[172:175], v[188:191], v[114:117]
	v_mfma_f32_16x16x32_bf16 v[102:105], v[164:167], v[196:199], v[102:105]
	v_mfma_f32_16x16x32_bf16 v[98:101], v[172:175], v[196:199], v[98:101]
	v_mfma_f32_16x16x32_bf16 v[86:89], v[164:167], v[204:207], v[86:89]
	v_mfma_f32_16x16x32_bf16 v[82:85], v[172:175], v[204:207], v[82:85]
	v_mfma_f32_16x16x32_bf16 v[70:73], v[164:167], v[212:215], v[70:73]
	v_mfma_f32_16x16x32_bf16 v[66:69], v[172:175], v[212:215], v[66:69]
	v_mfma_f32_16x16x32_bf16 v[118:121], v[168:171], v[192:195], v[118:121]
	v_mfma_f32_16x16x32_bf16 v[114:117], v[182:185], v[192:195], v[114:117]
	v_mfma_f32_16x16x32_bf16 v[102:105], v[168:171], v[200:203], v[102:105]
	v_mfma_f32_16x16x32_bf16 v[98:101], v[182:185], v[200:203], v[98:101]
	v_mfma_f32_16x16x32_bf16 v[86:89], v[168:171], v[208:211], v[86:89]
	v_mfma_f32_16x16x32_bf16 v[82:85], v[182:185], v[208:211], v[82:85]
	v_mfma_f32_16x16x32_bf16 v[70:73], v[168:171], v[216:219], v[70:73]
	v_mfma_f32_16x16x32_bf16 v[66:69], v[182:185], v[216:219], v[66:69]
	s_setprio 0
	s_barrier
	s_add_i32 s73, s73, s43
	v_lshl_add_u64 v[144:145], s[24:25], 0, v[0:1]
	s_mov_b32 m0, s73
	ds_read_b128 v[188:191], v150 offset:16384
	ds_read_b128 v[192:195], v150 offset:17408
	ds_read_b128 v[196:199], v150 offset:18432
	ds_read_b128 v[200:203], v150 offset:19456
	ds_read_b128 v[204:207], v150 offset:20480
	ds_read_b128 v[208:211], v150 offset:21504
	ds_read_b128 v[212:215], v150 offset:22528
	ds_read_b128 v[216:219], v150 offset:23552
	global_load_lds_dwordx4 v[144:145], off
	s_add_i32 m0, s73, 0x2000
	s_add_u32 s74, s24, 0x40000
	v_lshl_add_u64 v[176:177], s[24:25], 0, v[130:131]
	s_addc_u32 s75, s25, 0
	s_add_i32 s73, s76, s43
	global_load_lds_dwordx4 v[176:177], off
	v_lshl_add_u64 v[220:221], s[74:75], 0, v[0:1]
	s_mov_b32 m0, s73
	v_lshl_add_u64 v[222:223], s[30:31], 0, v[132:133]
	global_load_lds_dwordx4 v[220:221], off
	v_lshl_add_u64 v[220:221], s[74:75], 0, v[130:131]
	s_add_i32 m0, s73, 0x2000
	s_nop 0
	global_load_lds_dwordx4 v[220:221], off
	v_lshl_add_u64 v[220:221], s[30:31], 0, v[134:135]
	s_mov_b32 m0, s44
	s_nop 0
	global_load_lds_dwordx4 v[220:221], off
	s_mov_b32 m0, s45
	s_nop 0
	global_load_lds_dwordx4 v[222:223], off
	s_waitcnt vmcnt(8)
	s_waitcnt lgkmcnt(0)
	s_barrier
; #define PG8_STAGE(bufoff, gbase, voff) do { _Pragma("unroll") for (int _i = 0; _i < 2; ++_i) \
;         __builtin_amdgcn_global_load_lds((const unsigned*)((const char*)(gbase) + (voff)[_i]), (PG8_LAS unsigned*)(lds + (bufoff) + ldsw + _i * 8192), 16, 0, 0); } while (0)
; #define PG8_LDA(dst, b, h) do { _Pragma("unroll") for (int m = 0; m < 4; ++m) _Pragma("unroll") for (int k = 0; k < 2; ++k) dst[m][k] = *(const PG8_LAS bf16x8*)(lds + PG8_SA(b, h) + aoff + m * 2048 + k * 1024); } while (0)
; #define PG8_LDB(dst, b, h) do { _Pragma("unroll") for (int n = 0; n < 2; ++n) _Pragma("unroll") for (int k = 0; k < 2; ++k) dst[n][k] = *(const PG8_LAS bf16x8*)(lds + PG8_SB(b, h) + boff + n * 2048 + k * 1024); } while (0)
; #define PG8_MMA(ai, bj, At, Bt) do { __builtin_amdgcn_s_setprio(1); _Pragma("unroll") for (int m = 0; m < 4; ++m) _Pragma("unroll") for (int n = 0; n < 2; ++n) _Pragma("unroll") for (int k = 0; k < 2; ++k) \
;         acc[ai][bj][m][n] = __builtin_amdgcn_mfma_f32_16x16x32_bf16(Bt[n][k], At[m][k], acc[ai][bj][m][n], 0, 0, 0); __builtin_amdgcn_s_setprio(0); } while (0)
; #define PG8_WAIT_V(n) asm volatile("s_waitcnt vmcnt(" #n ")" ::: "memory")
; #define PG8_WAIT_L(n) asm volatile("s_waitcnt lgkmcnt(" #n ")" ::: "memory")
; #define PG8_BAR __builtin_amdgcn_s_barrier()
; #define PG8_SCHED __builtin_amdgcn_sched_barrier(0)
; template <class Epi, class Sched, bool ALIGN_EPI = false, bool SP2 = false>
; __device__ __forceinline__ void gemm_phase(PG8_LAS unsigned char* lds, const Gemm g, const Sched& S, const Epi& E) {
;     ...
;             PG8_WAIT_V(8); PG8_WAIT_L(0); PG8_BAR; PG8_MMA(1, 0, At, B0); PG8_MMA(1, 1, At, B1); PG8_BAR; PG8_SCHED;
;             PG8_LDB(B0, 1, 0); PG8_LDB(B1, 1, 1); PG8_SCHED; PG8_LDA(At, 1, 0); PG8_STAGE(PG8_SA(0, 1), a2 + hstep, voffA);
;             PG8_WAIT_V(8); PG8_WAIT_L(0); PG8_BAR; PG8_MMA(0, 0, At, B0); PG8_MMA(0, 1, At, B1); PG8_BAR; PG8_SCHED;
	s_setprio 1
	s_waitcnt lgkmcnt(0)
	v_mfma_f32_16x16x32_bf16 v[62:65], v[140:143], v[188:191], v[62:65]
	v_mfma_f32_16x16x32_bf16 v[58:61], v[156:159], v[188:191], v[58:61]
	v_mfma_f32_16x16x32_bf16 v[46:49], v[140:143], v[196:199], v[46:49]
	v_mfma_f32_16x16x32_bf16 v[42:45], v[156:159], v[196:199], v[42:45]
	v_mfma_f32_16x16x32_bf16 v[30:33], v[140:143], v[204:207], v[30:33]
	v_mfma_f32_16x16x32_bf16 v[26:29], v[156:159], v[204:207], v[26:29]
	v_mfma_f32_16x16x32_bf16 v[14:17], v[140:143], v[212:215], v[14:17]
	v_mfma_f32_16x16x32_bf16 v[10:13], v[156:159], v[212:215], v[10:13]
	v_mfma_f32_16x16x32_bf16 v[62:65], v[152:155], v[192:195], v[62:65]
	v_mfma_f32_16x16x32_bf16 v[58:61], v[160:163], v[192:195], v[58:61]
	v_mfma_f32_16x16x32_bf16 v[46:49], v[152:155], v[200:203], v[46:49]
	v_mfma_f32_16x16x32_bf16 v[42:45], v[160:163], v[200:203], v[42:45]
	v_mfma_f32_16x16x32_bf16 v[30:33], v[152:155], v[208:211], v[30:33]
	v_mfma_f32_16x16x32_bf16 v[26:29], v[160:163], v[208:211], v[26:29]
	v_mfma_f32_16x16x32_bf16 v[14:17], v[152:155], v[216:219], v[14:17]
	v_mfma_f32_16x16x32_bf16 v[10:13], v[160:163], v[216:219], v[10:13]
	s_setprio 0
	s_setprio 1
	v_mfma_f32_16x16x32_bf16 v[54:57], v[164:167], v[188:191], v[54:57]
	v_mfma_f32_16x16x32_bf16 v[50:53], v[172:175], v[188:191], v[50:53]
	v_mfma_f32_16x16x32_bf16 v[38:41], v[164:167], v[196:199], v[38:41]
	v_mfma_f32_16x16x32_bf16 v[34:37], v[172:175], v[196:199], v[34:37]
	v_mfma_f32_16x16x32_bf16 v[22:25], v[164:167], v[204:207], v[22:25]
	v_mfma_f32_16x16x32_bf16 v[18:21], v[172:175], v[204:207], v[18:21]
	v_mfma_f32_16x16x32_bf16 v[6:9], v[164:167], v[212:215], v[6:9]
	v_mfma_f32_16x16x32_bf16 v[2:5], v[172:175], v[212:215], v[2:5]
	v_mfma_f32_16x16x32_bf16 v[54:57], v[168:171], v[192:195], v[54:57]
	v_mfma_f32_16x16x32_bf16 v[50:53], v[182:185], v[192:195], v[50:53]
	v_mfma_f32_16x16x32_bf16 v[38:41], v[168:171], v[200:203], v[38:41]
	v_mfma_f32_16x16x32_bf16 v[34:37], v[182:185], v[200:203], v[34:37]
	v_mfma_f32_16x16x32_bf16 v[22:25], v[168:171], v[208:211], v[22:25]
	v_mfma_f32_16x16x32_bf16 v[18:21], v[182:185], v[208:211], v[18:21]
	v_mfma_f32_16x16x32_bf16 v[6:9], v[168:171], v[216:219], v[6:9]
	v_mfma_f32_16x16x32_bf16 v[2:5], v[182:185], v[216:219], v[2:5]
	s_setprio 0
	s_barrier
	s_add_i32 s73, 0, 0x18000
	v_add_u32_e32 v146, s73, v148
	s_add_i32 s74, 0, 0x1c000
	ds_read_b128 v[140:143], v146
	ds_read_b128 v[152:155], v146 offset:1024
	ds_read_b128 v[156:159], v146 offset:2048
	ds_read_b128 v[160:163], v146 offset:3072
	v_add_u32_e32 v146, s74, v148
	ds_read_b128 v[164:167], v146
	ds_read_b128 v[168:171], v146 offset:1024
	ds_read_b128 v[172:175], v146 offset:2048
	ds_read_b128 v[182:185], v146 offset:3072
	s_add_u32 s30, s30, 0x40000
	s_addc_u32 s31, s31, 0
	s_mov_b32 m0, s46
	v_lshl_add_u64 v[224:225], s[30:31], 0, v[134:135]
	ds_read_b128 v[188:191], v150 offset:32768
	ds_read_b128 v[192:195], v150 offset:33792
	ds_read_b128 v[196:199], v150 offset:34816
	ds_read_b128 v[200:203], v150 offset:35840
	ds_read_b128 v[204:207], v150 offset:36864
	ds_read_b128 v[208:211], v150 offset:37888
	ds_read_b128 v[212:215], v150 offset:38912
	ds_read_b128 v[216:219], v150 offset:39936
	global_load_lds_dwordx4 v[224:225], off
	v_lshl_add_u64 v[224:225], s[30:31], 0, v[132:133]
	s_mov_b32 m0, s47
	s_nop 0
	global_load_lds_dwordx4 v[224:225], off
	s_waitcnt vmcnt(8)
	s_waitcnt lgkmcnt(0)
	s_barrier
	s_setprio 1
	s_waitcnt lgkmcnt(0)
	v_mfma_f32_16x16x32_bf16 v[126:129], v[140:143], v[188:191], v[126:129]
	v_mfma_f32_16x16x32_bf16 v[122:125], v[156:159], v[188:191], v[122:125]
	v_mfma_f32_16x16x32_bf16 v[110:113], v[140:143], v[196:199], v[110:113]
	v_mfma_f32_16x16x32_bf16 v[106:109], v[156:159], v[196:199], v[106:109]
	v_mfma_f32_16x16x32_bf16 v[94:97], v[140:143], v[204:207], v[94:97]
	v_mfma_f32_16x16x32_bf16 v[90:93], v[156:159], v[204:207], v[90:93]
	v_mfma_f32_16x16x32_bf16 v[78:81], v[140:143], v[212:215], v[78:81]
	v_mfma_f32_16x16x32_bf16 v[74:77], v[156:159], v[212:215], v[74:77]
	v_mfma_f32_16x16x32_bf16 v[126:129], v[152:155], v[192:195], v[126:129]
	v_mfma_f32_16x16x32_bf16 v[122:125], v[160:163], v[192:195], v[122:125]
	v_mfma_f32_16x16x32_bf16 v[110:113], v[152:155], v[200:203], v[110:113]
	v_mfma_f32_16x16x32_bf16 v[106:109], v[160:163], v[200:203], v[106:109]
	v_mfma_f32_16x16x32_bf16 v[94:97], v[152:155], v[208:211], v[94:97]
	v_mfma_f32_16x16x32_bf16 v[90:93], v[160:163], v[208:211], v[90:93]
	v_mfma_f32_16x16x32_bf16 v[78:81], v[152:155], v[216:219], v[78:81]
	v_mfma_f32_16x16x32_bf16 v[74:77], v[160:163], v[216:219], v[74:77]
	s_setprio 0
	s_setprio 1
	v_mfma_f32_16x16x32_bf16 v[118:121], v[164:167], v[188:191], v[118:121]
	v_mfma_f32_16x16x32_bf16 v[114:117], v[172:175], v[188:191], v[114:117]
	v_mfma_f32_16x16x32_bf16 v[102:105], v[164:167], v[196:199], v[102:105]
	v_mfma_f32_16x16x32_bf16 v[98:101], v[172:175], v[196:199], v[98:101]
	v_mfma_f32_16x16x32_bf16 v[86:89], v[164:167], v[204:207], v[86:89]
	v_mfma_f32_16x16x32_bf16 v[82:85], v[172:175], v[204:207], v[82:85]
	v_mfma_f32_16x16x32_bf16 v[70:73], v[164:167], v[212:215], v[70:73]
	v_mfma_f32_16x16x32_bf16 v[66:69], v[172:175], v[212:215], v[66:69]
	v_mfma_f32_16x16x32_bf16 v[118:121], v[168:171], v[192:195], v[118:121]
	v_mfma_f32_16x16x32_bf16 v[114:117], v[182:185], v[192:195], v[114:117]
	v_mfma_f32_16x16x32_bf16 v[102:105], v[168:171], v[200:203], v[102:105]
	v_mfma_f32_16x16x32_bf16 v[98:101], v[182:185], v[200:203], v[98:101]
	v_mfma_f32_16x16x32_bf16 v[86:89], v[168:171], v[208:211], v[86:89]
	v_mfma_f32_16x16x32_bf16 v[82:85], v[182:185], v[208:211], v[82:85]
	v_mfma_f32_16x16x32_bf16 v[70:73], v[168:171], v[216:219], v[70:73]
	v_mfma_f32_16x16x32_bf16 v[66:69], v[182:185], v[216:219], v[66:69]
	s_setprio 0
	s_barrier
; #define PG8_STAGE(bufoff, gbase, voff) do { _Pragma("unroll") for (int _i = 0; _i < 2; ++_i) \
;         __builtin_amdgcn_global_load_lds((const unsigned*)((const char*)(gbase) + (voff)[_i]), (PG8_LAS unsigned*)(lds + (bufoff) + ldsw + _i * 8192), 16, 0, 0); } while (0)
; #define PG8_LDA(dst, b, h) do { _Pragma("unroll") for (int m = 0; m < 4; ++m) _Pragma("unroll") for (int k = 0; k < 2; ++k) dst[m][k] = *(const PG8_LAS bf16x8*)(lds + PG8_SA(b, h) + aoff + m * 2048 + k * 1024); } while (0)
; #define PG8_MMA(ai, bj, At, Bt) do { __builtin_amdgcn_s_setprio(1); _Pragma("unroll") for (int m = 0; m < 4; ++m) _Pragma("unroll") for (int n = 0; n < 2; ++n) _Pragma("unroll") for (int k = 0; k < 2; ++k) \
;         acc[ai][bj][m][n] = __builtin_amdgcn_mfma_f32_16x16x32_bf16(Bt[n][k], At[m][k], acc[ai][bj][m][n], 0, 0, 0); __builtin_amdgcn_s_setprio(0); } while (0)
; #define PG8_WAIT_V(n) asm volatile("s_waitcnt vmcnt(" #n ")" ::: "memory")
; #define PG8_WAIT_L(n) asm volatile("s_waitcnt lgkmcnt(" #n ")" ::: "memory")
; #define PG8_BAR __builtin_amdgcn_s_barrier()
; #define PG8_SCHED __builtin_amdgcn_sched_barrier(0)
; template <class Epi, class Sched, bool ALIGN_EPI = false, bool SP2 = false>
; __device__ __forceinline__ void gemm_phase(PG8_LAS unsigned char* lds, const Gemm g, const Sched& S, const Epi& E) {
;     ...
;         for (int t = 0; t < nt; t += 2) {
;             const bool last = (t == nt - 2);
;             const char* a1 = cA + (size_t)(t + 1) * kstep;
;             const char* a2 = last ? nA : cA + (size_t)(t + 2) * kstep; const char* b2 = last ? nB : cB + (size_t)(t + 2) * kstep;
;             const char* a3 = a2 + kstep; const char* b3 = b2 + kstep;
;     ...
;             PG8_LDA(At, 1, 1); PG8_STAGE(PG8_SB(1, 0), b3, voffB); PG8_STAGE(PG8_SB(1, 1), b3 + hstep, voffB); PG8_STAGE(PG8_SA(1, 0), a3, voffA);
;             PG8_WAIT_V(8); PG8_WAIT_L(0); PG8_BAR; PG8_MMA(1, 0, At, B0); PG8_MMA(1, 1, At, B1); PG8_BAR; PG8_SCHED;
	s_add_i32 s30, s73, s43
	v_lshl_add_u64 v[144:145], v[144:145], 0, s[66:67]
	s_mov_b32 m0, s30
	ds_read_b128 v[188:191], v150 offset:49152
	ds_read_b128 v[192:195], v150 offset:50176
	ds_read_b128 v[196:199], v150 offset:51200
	ds_read_b128 v[200:203], v150 offset:52224
	ds_read_b128 v[204:207], v150 offset:53248
	ds_read_b128 v[208:211], v150 offset:54272
	ds_read_b128 v[212:215], v150 offset:55296
	ds_read_b128 v[216:219], v150 offset:56320
	global_load_lds_dwordx4 v[144:145], off
	s_add_i32 m0, s30, 0x2000
	s_add_u32 s24, s24, 0x40080
	v_lshl_add_u64 v[144:145], v[176:177], 0, s[66:67]
	s_addc_u32 s25, s25, 0
	s_add_i32 s30, s74, s43
	global_load_lds_dwordx4 v[144:145], off
	v_lshl_add_u64 v[144:145], s[24:25], 0, v[0:1]
	s_mov_b32 m0, s30
	s_nop 0
	global_load_lds_dwordx4 v[144:145], off
	v_lshl_add_u64 v[144:145], s[24:25], 0, v[130:131]
	s_add_i32 m0, s30, 0x2000
	s_nop 0
	global_load_lds_dwordx4 v[144:145], off
	v_lshl_add_u64 v[144:145], v[220:221], 0, s[66:67]
	s_mov_b32 m0, s49
	s_nop 0
	global_load_lds_dwordx4 v[144:145], off
	v_lshl_add_u64 v[144:145], v[222:223], 0, s[66:67]
	s_mov_b32 m0, s50
	s_nop 0
	global_load_lds_dwordx4 v[144:145], off
	s_waitcnt vmcnt(8)
	s_waitcnt lgkmcnt(0)
	s_barrier
	s_setprio 1
	s_waitcnt lgkmcnt(0)
	v_mfma_f32_16x16x32_bf16 v[62:65], v[140:143], v[188:191], v[62:65]
	v_mfma_f32_16x16x32_bf16 v[58:61], v[156:159], v[188:191], v[58:61]
	v_mfma_f32_16x16x32_bf16 v[46:49], v[140:143], v[196:199], v[46:49]
	v_mfma_f32_16x16x32_bf16 v[42:45], v[156:159], v[196:199], v[42:45]
	v_mfma_f32_16x16x32_bf16 v[30:33], v[140:143], v[204:207], v[30:33]
	v_mfma_f32_16x16x32_bf16 v[26:29], v[156:159], v[204:207], v[26:29]
	v_mfma_f32_16x16x32_bf16 v[14:17], v[140:143], v[212:215], v[14:17]
	v_mfma_f32_16x16x32_bf16 v[10:13], v[156:159], v[212:215], v[10:13]
	v_mfma_f32_16x16x32_bf16 v[62:65], v[152:155], v[192:195], v[62:65]
	v_mfma_f32_16x16x32_bf16 v[58:61], v[160:163], v[192:195], v[58:61]
	v_mfma_f32_16x16x32_bf16 v[46:49], v[152:155], v[200:203], v[46:49]
	v_mfma_f32_16x16x32_bf16 v[42:45], v[160:163], v[200:203], v[42:45]
	v_mfma_f32_16x16x32_bf16 v[30:33], v[152:155], v[208:211], v[30:33]
	v_mfma_f32_16x16x32_bf16 v[26:29], v[160:163], v[208:211], v[26:29]
	v_mfma_f32_16x16x32_bf16 v[14:17], v[152:155], v[216:219], v[14:17]
	v_mfma_f32_16x16x32_bf16 v[10:13], v[160:163], v[216:219], v[10:13]
	s_setprio 0
	s_setprio 1
	v_mfma_f32_16x16x32_bf16 v[54:57], v[164:167], v[188:191], v[54:57]
	v_mfma_f32_16x16x32_bf16 v[50:53], v[172:175], v[188:191], v[50:53]
	v_mfma_f32_16x16x32_bf16 v[38:41], v[164:167], v[196:199], v[38:41]
	v_mfma_f32_16x16x32_bf16 v[34:37], v[172:175], v[196:199], v[34:37]
	v_mfma_f32_16x16x32_bf16 v[22:25], v[164:167], v[204:207], v[22:25]
	v_mfma_f32_16x16x32_bf16 v[18:21], v[172:175], v[204:207], v[18:21]
	v_mfma_f32_16x16x32_bf16 v[6:9], v[164:167], v[212:215], v[6:9]
	v_mfma_f32_16x16x32_bf16 v[2:5], v[172:175], v[212:215], v[2:5]
	v_mfma_f32_16x16x32_bf16 v[54:57], v[168:171], v[192:195], v[54:57]
	v_mfma_f32_16x16x32_bf16 v[50:53], v[182:185], v[192:195], v[50:53]
	v_mfma_f32_16x16x32_bf16 v[38:41], v[168:171], v[200:203], v[38:41]
	v_mfma_f32_16x16x32_bf16 v[34:37], v[182:185], v[200:203], v[34:37]
	v_mfma_f32_16x16x32_bf16 v[22:25], v[168:171], v[208:211], v[22:25]
	v_mfma_f32_16x16x32_bf16 v[18:21], v[182:185], v[208:211], v[18:21]
	v_mfma_f32_16x16x32_bf16 v[6:9], v[168:171], v[216:219], v[6:9]
	v_mfma_f32_16x16x32_bf16 v[2:5], v[182:185], v[216:219], v[2:5]
	s_setprio 0
	s_add_i32 s72, s72, 2
	s_add_u32 s22, s22, 0x100
	s_addc_u32 s23, s23, 0
	s_add_u32 s70, s70, 0x100
	s_addc_u32 s71, s71, 0
	s_add_u32 s24, s22, 0xfffc0080
	s_addc_u32 s25, s23, -1
	s_add_i32 s73, 0, 0x10000
	s_cmp_eq_u32 s72, 12
	s_cselect_b32 s31, s15, s25
	s_cselect_b32 s30, s68, s24
	s_cselect_b32 s25, s13, s71
	s_cselect_b32 s24, s69, s70
	s_add_i32 s76, 0, 0x14000
	s_cmp_gt_u32 s72, 13
	s_barrier
	s_cbranch_scc0 .Lrot_fu
	s_and_b64 vcc, exec, s[10:11]
	s_cbranch_vccz .LBB0_969
	s_barrier

; #define PG8_STAGE(bufoff, gbase, voff) do { _Pragma("unroll") for (int _i = 0; _i < 2; ++_i) \
;         __builtin_amdgcn_global_load_lds((const unsigned*)((const char*)(gbase) + (voff)[_i]), (PG8_LAS unsigned*)(lds + (bufoff) + ldsw + _i * 8192), 16, 0, 0); } while (0)
; #define PG8_LDA(dst, b, h) do { _Pragma("unroll") for (int m = 0; m < 4; ++m) _Pragma("unroll") for (int k = 0; k < 2; ++k) dst[m][k] = *(const PG8_LAS bf16x8*)(lds + PG8_SA(b, h) + aoff + m * 2048 + k * 1024); } while (0)
; #define PG8_LDB(dst, b, h) do { _Pragma("unroll") for (int n = 0; n < 2; ++n) _Pragma("unroll") for (int k = 0; k < 2; ++k) dst[n][k] = *(const PG8_LAS bf16x8*)(lds + PG8_SB(b, h) + boff + n * 2048 + k * 1024); } while (0)
; #define PG8_MMA(ai, bj, At, Bt) do { __builtin_amdgcn_s_setprio(1); _Pragma("unroll") for (int m = 0; m < 4; ++m) _Pragma("unroll") for (int n = 0; n < 2; ++n) _Pragma("unroll") for (int k = 0; k < 2; ++k) \
;         acc[ai][bj][m][n] = __builtin_amdgcn_mfma_f32_16x16x32_bf16(Bt[n][k], At[m][k], acc[ai][bj][m][n], 0, 0, 0); __builtin_amdgcn_s_setprio(0); } while (0)
; #define PG8_WAIT_V(n) asm volatile("s_waitcnt vmcnt(" #n ")" ::: "memory")
; #define PG8_WAIT_L(n) asm volatile("s_waitcnt lgkmcnt(" #n ")" ::: "memory")
; #define PG8_BAR __builtin_amdgcn_s_barrier()
; #define PG8_SCHED __builtin_amdgcn_sched_barrier(0)
; template <class Epi, class Sched, bool ALIGN_EPI = false, bool SP2 = false>
; __device__ __forceinline__ void gemm_phase(PG8_LAS unsigned char* lds, const Gemm g, const Sched& S, const Epi& E) {
;     ...
;             PG8_LDB(B0, 0, 0); PG8_LDB(B1, 0, 1); PG8_SCHED; PG8_LDA(At, 0, 0); PG8_STAGE(PG8_SA(1, 1), a1 + hstep, voffA);
;             PG8_WAIT_V(8); PG8_WAIT_L(0); PG8_BAR; PG8_MMA(0, 0, At, B0); PG8_MMA(0, 1, At, B1); PG8_BAR; PG8_SCHED;
;             PG8_LDA(At, 0, 1); PG8_STAGE(PG8_SB(0, 0), b2, voffB); PG8_STAGE(PG8_SB(0, 1), b2 + hstep, voffB); PG8_STAGE(PG8_SA(0, 0), a2, voffA);
;             PG8_WAIT_V(8); PG8_WAIT_L(0); PG8_BAR; PG8_MMA(1, 0, At, B0); PG8_MMA(1, 1, At, B1); PG8_BAR; PG8_SCHED;
.Lrot_fd:
	v_add_u32_e32 v94, s82, v159
	v_add_u32_e32 v156, s83, v159
	ds_read_b128 v[82:85], v94
	ds_read_b128 v[86:89], v94 offset:1024
	ds_read_b128 v[90:93], v94 offset:2048
	ds_read_b128 v[94:97], v94 offset:3072
	ds_read_b128 v[152:155], v156
	ds_read_b128 v[162:165], v156 offset:1024
	ds_read_b128 v[166:169], v156 offset:2048
	ds_read_b128 v[170:173], v156 offset:3072
	v_lshl_add_u64 v[156:157], s[6:7], 0, v[148:149]
	s_add_i32 m0, s70, 0xc000
	ds_read_b128 v[174:177], v161
	ds_read_b128 v[182:185], v161 offset:1024
	ds_read_b128 v[188:191], v161 offset:2048
	ds_read_b128 v[192:195], v161 offset:3072
	ds_read_b128 v[196:199], v161 offset:4096
	ds_read_b128 v[200:203], v161 offset:5120
	ds_read_b128 v[204:207], v161 offset:6144
	ds_read_b128 v[208:211], v161 offset:7168
	global_load_lds_dwordx4 v[156:157], off
	v_lshl_add_u64 v[156:157], s[6:7], 0, v[150:151]
	s_add_i32 m0, s70, 0xe000
	s_nop 0
	global_load_lds_dwordx4 v[156:157], off
	s_waitcnt vmcnt(8)
	s_waitcnt lgkmcnt(0)
	s_barrier
	s_setprio 1
	s_waitcnt lgkmcnt(0)
	v_mfma_f32_16x16x32_bf16 v[142:145], v[82:85], v[174:177], v[142:145]
	v_mfma_f32_16x16x32_bf16 v[138:141], v[90:93], v[174:177], v[138:141]
	v_mfma_f32_16x16x32_bf16 v[126:129], v[82:85], v[188:191], v[126:129]
	v_mfma_f32_16x16x32_bf16 v[122:125], v[90:93], v[188:191], v[122:125]
	v_mfma_f32_16x16x32_bf16 v[110:113], v[82:85], v[196:199], v[110:113]
	v_mfma_f32_16x16x32_bf16 v[106:109], v[90:93], v[196:199], v[106:109]
	v_mfma_f32_16x16x32_bf16 v[78:81], v[82:85], v[204:207], v[78:81]
	v_mfma_f32_16x16x32_bf16 v[74:77], v[90:93], v[204:207], v[74:77]
	v_mfma_f32_16x16x32_bf16 v[142:145], v[86:89], v[182:185], v[142:145]
	v_mfma_f32_16x16x32_bf16 v[138:141], v[94:97], v[182:185], v[138:141]
	v_mfma_f32_16x16x32_bf16 v[126:129], v[86:89], v[192:195], v[126:129]
	v_mfma_f32_16x16x32_bf16 v[122:125], v[94:97], v[192:195], v[122:125]
	v_mfma_f32_16x16x32_bf16 v[110:113], v[86:89], v[200:203], v[110:113]
	v_mfma_f32_16x16x32_bf16 v[106:109], v[94:97], v[200:203], v[106:109]
	v_mfma_f32_16x16x32_bf16 v[78:81], v[86:89], v[208:211], v[78:81]
	v_mfma_f32_16x16x32_bf16 v[74:77], v[94:97], v[208:211], v[74:77]
	s_setprio 0
	s_setprio 1
	v_mfma_f32_16x16x32_bf16 v[134:137], v[152:155], v[174:177], v[134:137]
	v_mfma_f32_16x16x32_bf16 v[130:133], v[166:169], v[174:177], v[130:133]
	v_mfma_f32_16x16x32_bf16 v[118:121], v[152:155], v[188:191], v[118:121]
	v_mfma_f32_16x16x32_bf16 v[114:117], v[166:169], v[188:191], v[114:117]
	v_mfma_f32_16x16x32_bf16 v[102:105], v[152:155], v[196:199], v[102:105]
	v_mfma_f32_16x16x32_bf16 v[98:101], v[166:169], v[196:199], v[98:101]
	v_mfma_f32_16x16x32_bf16 v[70:73], v[152:155], v[204:207], v[70:73]
	v_mfma_f32_16x16x32_bf16 v[66:69], v[166:169], v[204:207], v[66:69]
	v_mfma_f32_16x16x32_bf16 v[134:137], v[162:165], v[182:185], v[134:137]
	v_mfma_f32_16x16x32_bf16 v[130:133], v[170:173], v[182:185], v[130:133]
	v_mfma_f32_16x16x32_bf16 v[118:121], v[162:165], v[192:195], v[118:121]
	v_mfma_f32_16x16x32_bf16 v[114:117], v[170:173], v[192:195], v[114:117]
	v_mfma_f32_16x16x32_bf16 v[102:105], v[162:165], v[200:203], v[102:105]
	v_mfma_f32_16x16x32_bf16 v[98:101], v[170:173], v[200:203], v[98:101]
	v_mfma_f32_16x16x32_bf16 v[70:73], v[162:165], v[208:211], v[70:73]
	v_mfma_f32_16x16x32_bf16 v[66:69], v[170:173], v[208:211], v[66:69]
	s_setprio 0
	s_barrier
	s_add_i32 s6, s82, s69
	v_lshl_add_u64 v[156:157], s[46:47], 0, v[0:1]
	s_mov_b32 m0, s6
	ds_read_b128 v[174:177], v161 offset:16384
	ds_read_b128 v[182:185], v161 offset:17408
	ds_read_b128 v[188:191], v161 offset:18432
	ds_read_b128 v[192:195], v161 offset:19456
	ds_read_b128 v[196:199], v161 offset:20480
	ds_read_b128 v[200:203], v161 offset:21504
	ds_read_b128 v[204:207], v161 offset:22528
	ds_read_b128 v[208:211], v161 offset:23552
	global_load_lds_dwordx4 v[156:157], off
	s_add_i32 m0, s6, 0x2000
	s_add_u32 s6, s46, 0x100000
	v_lshl_add_u64 v[212:213], s[46:47], 0, v[146:147]
	s_addc_u32 s7, s47, 0
	s_add_i32 s82, s83, s69
	global_load_lds_dwordx4 v[212:213], off
	v_lshl_add_u64 v[214:215], s[6:7], 0, v[0:1]
	s_mov_b32 m0, s82
	v_lshl_add_u64 v[216:217], s[48:49], 0, v[146:147]
	global_load_lds_dwordx4 v[214:215], off
	v_lshl_add_u64 v[214:215], s[6:7], 0, v[146:147]
	s_add_i32 m0, s82, 0x2000
	s_nop 0
	global_load_lds_dwordx4 v[214:215], off
	v_lshl_add_u64 v[214:215], s[48:49], 0, v[0:1]
	s_mov_b32 m0, s70
	s_nop 0
	global_load_lds_dwordx4 v[214:215], off
	s_mov_b32 m0, s71
	s_nop 0
	global_load_lds_dwordx4 v[216:217], off
	s_waitcnt vmcnt(8)
	s_waitcnt lgkmcnt(0)
	s_barrier
; #define PG8_STAGE(bufoff, gbase, voff) do { _Pragma("unroll") for (int _i = 0; _i < 2; ++_i) \
;         __builtin_amdgcn_global_load_lds((const unsigned*)((const char*)(gbase) + (voff)[_i]), (PG8_LAS unsigned*)(lds + (bufoff) + ldsw + _i * 8192), 16, 0, 0); } while (0)
; #define PG8_LDA(dst, b, h) do { _Pragma("unroll") for (int m = 0; m < 4; ++m) _Pragma("unroll") for (int k = 0; k < 2; ++k) dst[m][k] = *(const PG8_LAS bf16x8*)(lds + PG8_SA(b, h) + aoff + m * 2048 + k * 1024); } while (0)
; #define PG8_LDB(dst, b, h) do { _Pragma("unroll") for (int n = 0; n < 2; ++n) _Pragma("unroll") for (int k = 0; k < 2; ++k) dst[n][k] = *(const PG8_LAS bf16x8*)(lds + PG8_SB(b, h) + boff + n * 2048 + k * 1024); } while (0)
; #define PG8_MMA(ai, bj, At, Bt) do { __builtin_amdgcn_s_setprio(1); _Pragma("unroll") for (int m = 0; m < 4; ++m) _Pragma("unroll") for (int n = 0; n < 2; ++n) _Pragma("unroll") for (int k = 0; k < 2; ++k) \
;         acc[ai][bj][m][n] = __builtin_amdgcn_mfma_f32_16x16x32_bf16(Bt[n][k], At[m][k], acc[ai][bj][m][n], 0, 0, 0); __builtin_amdgcn_s_setprio(0); } while (0)
; #define PG8_WAIT_V(n) asm volatile("s_waitcnt vmcnt(" #n ")" ::: "memory")
; #define PG8_WAIT_L(n) asm volatile("s_waitcnt lgkmcnt(" #n ")" ::: "memory")
; #define PG8_BAR __builtin_amdgcn_s_barrier()
; #define PG8_SCHED __builtin_amdgcn_sched_barrier(0)
; template <class Epi, class Sched, bool ALIGN_EPI = false, bool SP2 = false>
; __device__ __forceinline__ void gemm_phase(PG8_LAS unsigned char* lds, const Gemm g, const Sched& S, const Epi& E) {
;     ...
;             PG8_WAIT_V(8); PG8_WAIT_L(0); PG8_BAR; PG8_MMA(1, 0, At, B0); PG8_MMA(1, 1, At, B1); PG8_BAR; PG8_SCHED;
;             PG8_LDB(B0, 1, 0); PG8_LDB(B1, 1, 1); PG8_SCHED; PG8_LDA(At, 1, 0); PG8_STAGE(PG8_SA(0, 1), a2 + hstep, voffA);
;             PG8_WAIT_V(8); PG8_WAIT_L(0); PG8_BAR; PG8_MMA(0, 0, At, B0); PG8_MMA(0, 1, At, B1); PG8_BAR; PG8_SCHED;
	s_setprio 1
	s_waitcnt lgkmcnt(0)
	v_mfma_f32_16x16x32_bf16 v[62:65], v[82:85], v[174:177], v[62:65]
	v_mfma_f32_16x16x32_bf16 v[58:61], v[90:93], v[174:177], v[58:61]
	v_mfma_f32_16x16x32_bf16 v[46:49], v[82:85], v[188:191], v[46:49]
	v_mfma_f32_16x16x32_bf16 v[42:45], v[90:93], v[188:191], v[42:45]
	v_mfma_f32_16x16x32_bf16 v[30:33], v[82:85], v[196:199], v[30:33]
	v_mfma_f32_16x16x32_bf16 v[26:29], v[90:93], v[196:199], v[26:29]
	v_mfma_f32_16x16x32_bf16 v[14:17], v[82:85], v[204:207], v[14:17]
	v_mfma_f32_16x16x32_bf16 v[10:13], v[90:93], v[204:207], v[10:13]
	v_mfma_f32_16x16x32_bf16 v[62:65], v[86:89], v[182:185], v[62:65]
	v_mfma_f32_16x16x32_bf16 v[58:61], v[94:97], v[182:185], v[58:61]
	v_mfma_f32_16x16x32_bf16 v[46:49], v[86:89], v[192:195], v[46:49]
	v_mfma_f32_16x16x32_bf16 v[42:45], v[94:97], v[192:195], v[42:45]
	v_mfma_f32_16x16x32_bf16 v[30:33], v[86:89], v[200:203], v[30:33]
	v_mfma_f32_16x16x32_bf16 v[26:29], v[94:97], v[200:203], v[26:29]
	v_mfma_f32_16x16x32_bf16 v[14:17], v[86:89], v[208:211], v[14:17]
	v_mfma_f32_16x16x32_bf16 v[10:13], v[94:97], v[208:211], v[10:13]
	s_setprio 0
	s_setprio 1
	v_mfma_f32_16x16x32_bf16 v[54:57], v[152:155], v[174:177], v[54:57]
	v_mfma_f32_16x16x32_bf16 v[50:53], v[166:169], v[174:177], v[50:53]
	v_mfma_f32_16x16x32_bf16 v[38:41], v[152:155], v[188:191], v[38:41]
	v_mfma_f32_16x16x32_bf16 v[34:37], v[166:169], v[188:191], v[34:37]
	v_mfma_f32_16x16x32_bf16 v[22:25], v[152:155], v[196:199], v[22:25]
	v_mfma_f32_16x16x32_bf16 v[18:21], v[166:169], v[196:199], v[18:21]
	v_mfma_f32_16x16x32_bf16 v[6:9], v[152:155], v[204:207], v[6:9]
	v_mfma_f32_16x16x32_bf16 v[2:5], v[166:169], v[204:207], v[2:5]
	v_mfma_f32_16x16x32_bf16 v[54:57], v[162:165], v[182:185], v[54:57]
	v_mfma_f32_16x16x32_bf16 v[50:53], v[170:173], v[182:185], v[50:53]
	v_mfma_f32_16x16x32_bf16 v[38:41], v[162:165], v[192:195], v[38:41]
	v_mfma_f32_16x16x32_bf16 v[34:37], v[170:173], v[192:195], v[34:37]
	v_mfma_f32_16x16x32_bf16 v[22:25], v[162:165], v[200:203], v[22:25]
	v_mfma_f32_16x16x32_bf16 v[18:21], v[170:173], v[200:203], v[18:21]
	v_mfma_f32_16x16x32_bf16 v[6:9], v[162:165], v[208:211], v[6:9]
	v_mfma_f32_16x16x32_bf16 v[2:5], v[170:173], v[208:211], v[2:5]
	s_setprio 0
	s_barrier
	s_add_i32 s82, 0, 0x18000
	s_add_i32 s83, 0, 0x1c000
	v_add_u32_e32 v94, s82, v159
	v_add_u32_e32 v170, s83, v159
	ds_read_b128 v[82:85], v94
	ds_read_b128 v[86:89], v94 offset:1024
	ds_read_b128 v[90:93], v94 offset:2048
	ds_read_b128 v[94:97], v94 offset:3072
	ds_read_b128 v[152:155], v170
	ds_read_b128 v[162:165], v170 offset:1024
	ds_read_b128 v[166:169], v170 offset:2048
	ds_read_b128 v[170:173], v170 offset:3072
	s_add_u32 s6, s48, 0x100000
	s_addc_u32 s7, s49, 0
	s_mov_b32 m0, s72
	v_lshl_add_u64 v[218:219], s[6:7], 0, v[0:1]
	ds_read_b128 v[174:177], v161 offset:32768
	ds_read_b128 v[182:185], v161 offset:33792
	ds_read_b128 v[188:191], v161 offset:34816
	ds_read_b128 v[192:195], v161 offset:35840
	ds_read_b128 v[196:199], v161 offset:36864
	ds_read_b128 v[200:203], v161 offset:37888
	ds_read_b128 v[204:207], v161 offset:38912
	ds_read_b128 v[208:211], v161 offset:39936
	global_load_lds_dwordx4 v[218:219], off
	v_lshl_add_u64 v[218:219], s[6:7], 0, v[146:147]
	s_mov_b32 m0, s73
	s_nop 0
	global_load_lds_dwordx4 v[218:219], off
	s_waitcnt vmcnt(8)
	s_waitcnt lgkmcnt(0)
	s_barrier
	s_setprio 1
	s_waitcnt lgkmcnt(0)
	v_mfma_f32_16x16x32_bf16 v[142:145], v[82:85], v[174:177], v[142:145]
	v_mfma_f32_16x16x32_bf16 v[138:141], v[90:93], v[174:177], v[138:141]
	v_mfma_f32_16x16x32_bf16 v[126:129], v[82:85], v[188:191], v[126:129]
	v_mfma_f32_16x16x32_bf16 v[122:125], v[90:93], v[188:191], v[122:125]
	v_mfma_f32_16x16x32_bf16 v[110:113], v[82:85], v[196:199], v[110:113]
	v_mfma_f32_16x16x32_bf16 v[106:109], v[90:93], v[196:199], v[106:109]
	v_mfma_f32_16x16x32_bf16 v[78:81], v[82:85], v[204:207], v[78:81]
	v_mfma_f32_16x16x32_bf16 v[74:77], v[90:93], v[204:207], v[74:77]
	v_mfma_f32_16x16x32_bf16 v[142:145], v[86:89], v[182:185], v[142:145]
	v_mfma_f32_16x16x32_bf16 v[138:141], v[94:97], v[182:185], v[138:141]
	v_mfma_f32_16x16x32_bf16 v[126:129], v[86:89], v[192:195], v[126:129]
	v_mfma_f32_16x16x32_bf16 v[122:125], v[94:97], v[192:195], v[122:125]
	v_mfma_f32_16x16x32_bf16 v[110:113], v[86:89], v[200:203], v[110:113]
	v_mfma_f32_16x16x32_bf16 v[106:109], v[94:97], v[200:203], v[106:109]
	v_mfma_f32_16x16x32_bf16 v[78:81], v[86:89], v[208:211], v[78:81]
	v_mfma_f32_16x16x32_bf16 v[74:77], v[94:97], v[208:211], v[74:77]
	s_setprio 0
	s_setprio 1
	v_mfma_f32_16x16x32_bf16 v[134:137], v[152:155], v[174:177], v[134:137]
	v_mfma_f32_16x16x32_bf16 v[130:133], v[166:169], v[174:177], v[130:133]
	v_mfma_f32_16x16x32_bf16 v[118:121], v[152:155], v[188:191], v[118:121]
	v_mfma_f32_16x16x32_bf16 v[114:117], v[166:169], v[188:191], v[114:117]
	v_mfma_f32_16x16x32_bf16 v[102:105], v[152:155], v[196:199], v[102:105]
	v_mfma_f32_16x16x32_bf16 v[98:101], v[166:169], v[196:199], v[98:101]
	v_mfma_f32_16x16x32_bf16 v[70:73], v[152:155], v[204:207], v[70:73]
	v_mfma_f32_16x16x32_bf16 v[66:69], v[166:169], v[204:207], v[66:69]
	v_mfma_f32_16x16x32_bf16 v[134:137], v[162:165], v[182:185], v[134:137]
	v_mfma_f32_16x16x32_bf16 v[130:133], v[170:173], v[182:185], v[130:133]
	v_mfma_f32_16x16x32_bf16 v[118:121], v[162:165], v[192:195], v[118:121]
	v_mfma_f32_16x16x32_bf16 v[114:117], v[170:173], v[192:195], v[114:117]
	v_mfma_f32_16x16x32_bf16 v[102:105], v[162:165], v[200:203], v[102:105]
	v_mfma_f32_16x16x32_bf16 v[98:101], v[170:173], v[200:203], v[98:101]
	v_mfma_f32_16x16x32_bf16 v[70:73], v[162:165], v[208:211], v[70:73]
	v_mfma_f32_16x16x32_bf16 v[66:69], v[170:173], v[208:211], v[66:69]
	s_setprio 0
	s_barrier
; #define PG8_STAGE(bufoff, gbase, voff) do { _Pragma("unroll") for (int _i = 0; _i < 2; ++_i) \
;         __builtin_amdgcn_global_load_lds((const unsigned*)((const char*)(gbase) + (voff)[_i]), (PG8_LAS unsigned*)(lds + (bufoff) + ldsw + _i * 8192), 16, 0, 0); } while (0)
; #define PG8_LDA(dst, b, h) do { _Pragma("unroll") for (int m = 0; m < 4; ++m) _Pragma("unroll") for (int k = 0; k < 2; ++k) dst[m][k] = *(const PG8_LAS bf16x8*)(lds + PG8_SA(b, h) + aoff + m * 2048 + k * 1024); } while (0)
; #define PG8_MMA(ai, bj, At, Bt) do { __builtin_amdgcn_s_setprio(1); _Pragma("unroll") for (int m = 0; m < 4; ++m) _Pragma("unroll") for (int n = 0; n < 2; ++n) _Pragma("unroll") for (int k = 0; k < 2; ++k) \
;         acc[ai][bj][m][n] = __builtin_amdgcn_mfma_f32_16x16x32_bf16(Bt[n][k], At[m][k], acc[ai][bj][m][n], 0, 0, 0); __builtin_amdgcn_s_setprio(0); } while (0)
; #define PG8_WAIT_V(n) asm volatile("s_waitcnt vmcnt(" #n ")" ::: "memory")
; #define PG8_WAIT_L(n) asm volatile("s_waitcnt lgkmcnt(" #n ")" ::: "memory")
; #define PG8_BAR __builtin_amdgcn_s_barrier()
; #define PG8_SCHED __builtin_amdgcn_sched_barrier(0)
; template <class Epi, class Sched, bool ALIGN_EPI = false, bool SP2 = false>
; __device__ __forceinline__ void gemm_phase(PG8_LAS unsigned char* lds, const Gemm g, const Sched& S, const Epi& E) {
;     ...
;         for (int t = 0; t < nt; t += 2) {
;             const bool last = (t == nt - 2);
;             const char* a1 = cA + (size_t)(t + 1) * kstep;
;             const char* a2 = last ? nA : cA + (size_t)(t + 2) * kstep; const char* b2 = last ? nB : cB + (size_t)(t + 2) * kstep;
;             const char* a3 = a2 + kstep; const char* b3 = b2 + kstep;
;     ...
;             PG8_LDA(At, 1, 1); PG8_STAGE(PG8_SB(1, 0), b3, voffB); PG8_STAGE(PG8_SB(1, 1), b3 + hstep, voffB); PG8_STAGE(PG8_SA(1, 0), a3, voffA);
;             PG8_WAIT_V(8); PG8_WAIT_L(0); PG8_BAR; PG8_MMA(1, 0, At, B0); PG8_MMA(1, 1, At, B1); PG8_BAR; PG8_SCHED;
	s_add_i32 s6, s82, s69
	v_lshl_add_u64 v[156:157], v[156:157], 0, s[66:67]
	s_mov_b32 m0, s6
	ds_read_b128 v[174:177], v161 offset:49152
	ds_read_b128 v[182:185], v161 offset:50176
	ds_read_b128 v[188:191], v161 offset:51200
	ds_read_b128 v[192:195], v161 offset:52224
	ds_read_b128 v[196:199], v161 offset:53248
	ds_read_b128 v[200:203], v161 offset:54272
	ds_read_b128 v[204:207], v161 offset:55296
	ds_read_b128 v[208:211], v161 offset:56320
	global_load_lds_dwordx4 v[156:157], off
	s_add_i32 m0, s6, 0x2000
	s_add_u32 s6, s46, 0x100080
	v_lshl_add_u64 v[156:157], v[212:213], 0, s[66:67]
	s_addc_u32 s7, s47, 0
	s_add_i32 s46, s83, s69
	global_load_lds_dwordx4 v[156:157], off
	v_lshl_add_u64 v[156:157], s[6:7], 0, v[0:1]
	s_mov_b32 m0, s46
	s_nop 0
	global_load_lds_dwordx4 v[156:157], off
	v_lshl_add_u64 v[156:157], s[6:7], 0, v[146:147]
	s_add_i32 m0, s46, 0x2000
	s_nop 0
	global_load_lds_dwordx4 v[156:157], off
	v_lshl_add_u64 v[156:157], v[214:215], 0, s[66:67]
	s_mov_b32 m0, s75
	s_nop 0
	global_load_lds_dwordx4 v[156:157], off
	v_lshl_add_u64 v[156:157], v[216:217], 0, s[66:67]
	s_mov_b32 m0, s76
	s_nop 0
	global_load_lds_dwordx4 v[156:157], off
	s_waitcnt vmcnt(8)
	s_waitcnt lgkmcnt(0)
	s_barrier
	s_setprio 1
	s_waitcnt lgkmcnt(0)
	v_mfma_f32_16x16x32_bf16 v[62:65], v[82:85], v[174:177], v[62:65]
	v_mfma_f32_16x16x32_bf16 v[58:61], v[90:93], v[174:177], v[58:61]
	v_mfma_f32_16x16x32_bf16 v[46:49], v[82:85], v[188:191], v[46:49]
	v_mfma_f32_16x16x32_bf16 v[42:45], v[90:93], v[188:191], v[42:45]
	v_mfma_f32_16x16x32_bf16 v[30:33], v[82:85], v[196:199], v[30:33]
	v_mfma_f32_16x16x32_bf16 v[26:29], v[90:93], v[196:199], v[26:29]
	v_mfma_f32_16x16x32_bf16 v[14:17], v[82:85], v[204:207], v[14:17]
	v_mfma_f32_16x16x32_bf16 v[10:13], v[90:93], v[204:207], v[10:13]
	v_mfma_f32_16x16x32_bf16 v[62:65], v[86:89], v[182:185], v[62:65]
	v_mfma_f32_16x16x32_bf16 v[58:61], v[94:97], v[182:185], v[58:61]
	v_mfma_f32_16x16x32_bf16 v[46:49], v[86:89], v[192:195], v[46:49]
	v_mfma_f32_16x16x32_bf16 v[42:45], v[94:97], v[192:195], v[42:45]
	v_mfma_f32_16x16x32_bf16 v[30:33], v[86:89], v[200:203], v[30:33]
	v_mfma_f32_16x16x32_bf16 v[26:29], v[94:97], v[200:203], v[26:29]
	v_mfma_f32_16x16x32_bf16 v[14:17], v[86:89], v[208:211], v[14:17]
	v_mfma_f32_16x16x32_bf16 v[10:13], v[94:97], v[208:211], v[10:13]
	s_setprio 0
	s_setprio 1
	v_mfma_f32_16x16x32_bf16 v[54:57], v[152:155], v[174:177], v[54:57]
	v_mfma_f32_16x16x32_bf16 v[50:53], v[166:169], v[174:177], v[50:53]
	v_mfma_f32_16x16x32_bf16 v[38:41], v[152:155], v[188:191], v[38:41]
	v_mfma_f32_16x16x32_bf16 v[34:37], v[166:169], v[188:191], v[34:37]
	v_mfma_f32_16x16x32_bf16 v[22:25], v[152:155], v[196:199], v[22:25]
	v_mfma_f32_16x16x32_bf16 v[18:21], v[166:169], v[196:199], v[18:21]
	v_mfma_f32_16x16x32_bf16 v[6:9], v[152:155], v[204:207], v[6:9]
	v_mfma_f32_16x16x32_bf16 v[2:5], v[166:169], v[204:207], v[2:5]
	v_mfma_f32_16x16x32_bf16 v[54:57], v[162:165], v[182:185], v[54:57]
	v_mfma_f32_16x16x32_bf16 v[50:53], v[170:173], v[182:185], v[50:53]
	v_mfma_f32_16x16x32_bf16 v[38:41], v[162:165], v[192:195], v[38:41]
	v_mfma_f32_16x16x32_bf16 v[34:37], v[170:173], v[192:195], v[34:37]
	v_mfma_f32_16x16x32_bf16 v[22:25], v[162:165], v[200:203], v[22:25]
	v_mfma_f32_16x16x32_bf16 v[18:21], v[170:173], v[200:203], v[18:21]
	v_mfma_f32_16x16x32_bf16 v[6:9], v[162:165], v[208:211], v[6:9]
	v_mfma_f32_16x16x32_bf16 v[2:5], v[170:173], v[208:211], v[2:5]
	s_setprio 0
	s_add_i32 s81, s81, 2
	s_add_u32 s43, s43, 0x100
	s_addc_u32 s80, s80, 0
	s_mov_b64 s[6:7], s[44:45]
	s_add_u32 s44, s6, 0x100
	s_addc_u32 s45, s7, 0
	s_add_i32 s82, 0, 0x10000
	s_cmp_eq_u32 s81, 60
	s_cselect_b32 s49, s25, s45
	s_cselect_b32 s48, s26, s44
	s_cselect_b32 s47, s23, s80
	s_cselect_b32 s46, s41, s43
	s_add_i32 s83, 0, 0x14000
	s_cmp_gt_u32 s81, 61
	s_barrier
	s_cbranch_scc0 .Lrot_fd
	s_and_b64 vcc, exec, s[20:21]
	s_cbranch_vccz .LBB0_1043
	s_barrier
